# v039 + GEMM K-loops: s_setprio 2 for the loading wave during the two 8-read/6-piece load segments (the critical ones per the sleep probes); compute start still sets 1
# baseline (speedup 1.0000x reference)
; #define PG8_STAGE(bufoff, gbase, voff) do { _Pragma("unroll") for (int _i = 0; _i < 2; ++_i) \
;         __builtin_amdgcn_global_load_lds((const unsigned*)((const char*)(gbase) + (voff)[_i]), (PG8_LAS unsigned*)(lds + (bufoff) + ldsw + _i * 8192), 16, 0, 0); } while (0)
; #define PG8_LDA(dst, b, h) do { _Pragma("unroll") for (int m = 0; m < 4; ++m) _Pragma("unroll") for (int k = 0; k < 2; ++k) dst[m][k] = *(const PG8_LAS bf16x8*)(lds + PG8_SA(b, h) + aoff + m * 2048 + k * 1024); } while (0)
; #define PG8_LDB(dst, b, h) do { _Pragma("unroll") for (int n = 0; n < 2; ++n) _Pragma("unroll") for (int k = 0; k < 2; ++k) dst[n][k] = *(const PG8_LAS bf16x8*)(lds + PG8_SB(b, h) + boff + n * 2048 + k * 1024); } while (0)
; #define PG8_MMA(ai, bj, At, Bt) do { __builtin_amdgcn_s_setprio(1); _Pragma("unroll") for (int m = 0; m < 4; ++m) _Pragma("unroll") for (int n = 0; n < 2; ++n) _Pragma("unroll") for (int k = 0; k < 2; ++k) \
;         acc[ai][bj][m][n] = __builtin_amdgcn_mfma_f32_16x16x32_bf16(Bt[n][k], At[m][k], acc[ai][bj][m][n], 0, 0, 0); __builtin_amdgcn_s_setprio(0); } while (0)
; #define PG8_WAIT_V(n) asm volatile("s_waitcnt vmcnt(" #n ")" ::: "memory")
; #define PG8_WAIT_L(n) asm volatile("s_waitcnt lgkmcnt(" #n ")" ::: "memory")
; #define PG8_BAR __builtin_amdgcn_s_barrier()
; #define PG8_SCHED __builtin_amdgcn_sched_barrier(0)
; template <class Epi, class Sched, bool ALIGN_EPI = false, bool SP2 = false>
; __device__ __forceinline__ void gemm_phase(PG8_LAS unsigned char* lds, const Gemm g, const Sched& S, const Epi& E) {
;     ...
;             const bool last = (t == nt - 2);
;             const char* a1 = cA + (size_t)(t + 1) * kstep;
;             const char* a2 = last ? nA : cA + (size_t)(t + 2) * kstep; const char* b2 = last ? nB : cB + (size_t)(t + 2) * kstep;
;             const char* a3 = a2 + kstep; const char* b3 = b2 + kstep;
;             if (last && has_next) S.a_ready(nxt);
;             if constexpr (SP2) {
;             PG8_LDB(B0, 0, 0); PG8_LDB(B1, 0, 1); PG8_SCHED; PG8_LDA(At, 0, 0); PG8_STAGE(PG8_SA(1, 1), a1 + hstep, voffA);
;             PG8_WAIT_V(8); PG8_WAIT_L(0); PG8_BAR; PG8_MMA(0, 0, At, B0); PG8_MMA(0, 1, At, B1); PG8_BAR; PG8_SCHED;
;             PG8_LDA(At, 0, 1); PG8_STAGE(PG8_SB(0, 0), b2, voffB); PG8_STAGE(PG8_SB(0, 1), b2 + hstep, voffB); PG8_STAGE(PG8_SA(0, 0), a2, voffA);
.LBB0_150:
	ds_read_b128 v[154:157], v150
	ds_read_b128 v[158:161], v150 offset:1024
	ds_read_b128 v[162:165], v150 offset:2048
	ds_read_b128 v[172:175], v150 offset:3072
	ds_read_b128 v[176:179], v151
	ds_read_b128 v[180:183], v151 offset:1024
	ds_read_b128 v[184:187], v151 offset:2048
	ds_read_b128 v[188:191], v151 offset:3072
	s_add_u32 s28, s0, 0xfffc0080
	s_addc_u32 s29, s1, -1
	s_cmp_eq_u32 s51, 12
	s_cselect_b32 s31, s21, s29
	s_cselect_b32 s30, s47, s28
	s_cselect_b32 s29, s19, s50
	s_cselect_b32 s28, s48, s49
	v_lshl_add_u64 v[144:145], s[0:1], 0, v[136:137]
	s_add_i32 m0, s27, 0xc000
	ds_read_b128 v[202:205], v152
	ds_read_b128 v[206:209], v152 offset:1024
	ds_read_b128 v[210:213], v152 offset:2048
	ds_read_b128 v[214:217], v152 offset:3072
	ds_read_b128 v[218:221], v152 offset:4096
	ds_read_b128 v[222:225], v152 offset:5120
	ds_read_b128 v[226:229], v152 offset:6144
	ds_read_b128 v[230:233], v152 offset:7168
	global_load_lds_dwordx4 v[144:145], off
	v_lshl_add_u64 v[144:145], s[0:1], 0, v[138:139]
	s_add_i32 m0, s27, 0xe000
	s_nop 0
	global_load_lds_dwordx4 v[144:145], off
	s_waitcnt vmcnt(8)
	s_waitcnt lgkmcnt(0)
	s_barrier
	s_setprio 1
	s_waitcnt lgkmcnt(0)
	v_mfma_f32_16x16x32_bf16 v[124:127], v[154:157], v[202:205], v[124:127]
	v_mfma_f32_16x16x32_bf16 v[120:123], v[162:165], v[202:205], v[120:123]
	v_mfma_f32_16x16x32_bf16 v[108:111], v[154:157], v[210:213], v[108:111]
	v_mfma_f32_16x16x32_bf16 v[104:107], v[162:165], v[210:213], v[104:107]
	v_mfma_f32_16x16x32_bf16 v[92:95], v[154:157], v[218:221], v[92:95]
	v_mfma_f32_16x16x32_bf16 v[88:91], v[162:165], v[218:221], v[88:91]
	v_mfma_f32_16x16x32_bf16 v[76:79], v[154:157], v[226:229], v[76:79]
	v_mfma_f32_16x16x32_bf16 v[72:75], v[162:165], v[226:229], v[72:75]
	v_mfma_f32_16x16x32_bf16 v[124:127], v[158:161], v[206:209], v[124:127]
	v_mfma_f32_16x16x32_bf16 v[120:123], v[172:175], v[206:209], v[120:123]
	v_mfma_f32_16x16x32_bf16 v[108:111], v[158:161], v[214:217], v[108:111]
	v_mfma_f32_16x16x32_bf16 v[104:107], v[172:175], v[214:217], v[104:107]
	v_mfma_f32_16x16x32_bf16 v[92:95], v[158:161], v[222:225], v[92:95]
	v_mfma_f32_16x16x32_bf16 v[88:91], v[172:175], v[222:225], v[88:91]
	v_mfma_f32_16x16x32_bf16 v[76:79], v[158:161], v[230:233], v[76:79]
	v_mfma_f32_16x16x32_bf16 v[72:75], v[172:175], v[230:233], v[72:75]
	s_setprio 0
	s_setprio 1
	v_mfma_f32_16x16x32_bf16 v[116:119], v[176:179], v[202:205], v[116:119]
	v_mfma_f32_16x16x32_bf16 v[112:115], v[184:187], v[202:205], v[112:115]
	v_mfma_f32_16x16x32_bf16 v[100:103], v[176:179], v[210:213], v[100:103]
	v_mfma_f32_16x16x32_bf16 v[96:99], v[184:187], v[210:213], v[96:99]
	v_mfma_f32_16x16x32_bf16 v[84:87], v[176:179], v[218:221], v[84:87]
	v_mfma_f32_16x16x32_bf16 v[80:83], v[184:187], v[218:221], v[80:83]
	v_mfma_f32_16x16x32_bf16 v[68:71], v[176:179], v[226:229], v[68:71]
	v_mfma_f32_16x16x32_bf16 v[64:67], v[184:187], v[226:229], v[64:67]
	v_mfma_f32_16x16x32_bf16 v[116:119], v[180:183], v[206:209], v[116:119]
	v_mfma_f32_16x16x32_bf16 v[112:115], v[188:191], v[206:209], v[112:115]
	v_mfma_f32_16x16x32_bf16 v[100:103], v[180:183], v[214:217], v[100:103]
	v_mfma_f32_16x16x32_bf16 v[96:99], v[188:191], v[214:217], v[96:99]
	v_mfma_f32_16x16x32_bf16 v[84:87], v[180:183], v[222:225], v[84:87]
	v_mfma_f32_16x16x32_bf16 v[80:83], v[188:191], v[222:225], v[80:83]
	v_mfma_f32_16x16x32_bf16 v[68:71], v[180:183], v[230:233], v[68:71]
	v_mfma_f32_16x16x32_bf16 v[64:67], v[188:191], v[230:233], v[64:67]
	s_setprio 0
	s_barrier
	s_setprio 2
	s_add_i32 s52, s44, s34
	v_lshl_add_u64 v[144:145], s[28:29], 0, v[132:133]
	s_mov_b32 m0, s52
	ds_read_b128 v[202:205], v152 offset:16384
	ds_read_b128 v[206:209], v152 offset:17408
	ds_read_b128 v[210:213], v152 offset:18432
	ds_read_b128 v[214:217], v152 offset:19456
	ds_read_b128 v[218:221], v152 offset:20480
	ds_read_b128 v[222:225], v152 offset:21504
	ds_read_b128 v[226:229], v152 offset:22528
	ds_read_b128 v[230:233], v152 offset:23552
	global_load_lds_dwordx4 v[144:145], off
	s_add_i32 m0, s52, 0x2000
	s_add_u32 s52, s28, 0x40000
	v_lshl_add_u64 v[166:167], s[28:29], 0, v[128:129]
	s_addc_u32 s53, s29, 0
	s_add_i32 s54, s45, s34
	global_load_lds_dwordx4 v[166:167], off
	v_lshl_add_u64 v[192:193], s[52:53], 0, v[132:133]
	s_mov_b32 m0, s54
	v_lshl_add_u64 v[196:197], s[30:31], 0, v[130:131]
	global_load_lds_dwordx4 v[192:193], off
	v_lshl_add_u64 v[192:193], s[52:53], 0, v[128:129]
	s_add_i32 m0, s54, 0x2000
	s_nop 0
	global_load_lds_dwordx4 v[192:193], off
	v_lshl_add_u64 v[192:193], s[30:31], 0, v[134:135]
	s_mov_b32 m0, s27
	s_nop 0
	global_load_lds_dwordx4 v[192:193], off
	s_mov_b32 m0, s37
	s_nop 0
	global_load_lds_dwordx4 v[196:197], off
	s_waitcnt vmcnt(8)
	s_waitcnt lgkmcnt(0)
	s_barrier
; #define PG8_STAGE(bufoff, gbase, voff) do { _Pragma("unroll") for (int _i = 0; _i < 2; ++_i) \
;         __builtin_amdgcn_global_load_lds((const unsigned*)((const char*)(gbase) + (voff)[_i]), (PG8_LAS unsigned*)(lds + (bufoff) + ldsw + _i * 8192), 16, 0, 0); } while (0)
; #define PG8_LDA(dst, b, h) do { _Pragma("unroll") for (int m = 0; m < 4; ++m) _Pragma("unroll") for (int k = 0; k < 2; ++k) dst[m][k] = *(const PG8_LAS bf16x8*)(lds + PG8_SA(b, h) + aoff + m * 2048 + k * 1024); } while (0)
; #define PG8_LDB(dst, b, h) do { _Pragma("unroll") for (int n = 0; n < 2; ++n) _Pragma("unroll") for (int k = 0; k < 2; ++k) dst[n][k] = *(const PG8_LAS bf16x8*)(lds + PG8_SB(b, h) + boff + n * 2048 + k * 1024); } while (0)
; #define PG8_MMA(ai, bj, At, Bt) do { __builtin_amdgcn_s_setprio(1); _Pragma("unroll") for (int m = 0; m < 4; ++m) _Pragma("unroll") for (int n = 0; n < 2; ++n) _Pragma("unroll") for (int k = 0; k < 2; ++k) \
;         acc[ai][bj][m][n] = __builtin_amdgcn_mfma_f32_16x16x32_bf16(Bt[n][k], At[m][k], acc[ai][bj][m][n], 0, 0, 0); __builtin_amdgcn_s_setprio(0); } while (0)
; #define PG8_WAIT_V(n) asm volatile("s_waitcnt vmcnt(" #n ")" ::: "memory")
; #define PG8_WAIT_L(n) asm volatile("s_waitcnt lgkmcnt(" #n ")" ::: "memory")
; #define PG8_BAR __builtin_amdgcn_s_barrier()
; #define PG8_SCHED __builtin_amdgcn_sched_barrier(0)
; template <class Epi, class Sched, bool ALIGN_EPI = false, bool SP2 = false>
; __device__ __forceinline__ void gemm_phase(PG8_LAS unsigned char* lds, const Gemm g, const Sched& S, const Epi& E) {
;     ...
;             PG8_WAIT_V(8); PG8_WAIT_L(0); PG8_BAR; PG8_MMA(1, 0, At, B0); PG8_MMA(1, 1, At, B1); PG8_BAR; PG8_SCHED;
;             PG8_LDB(B0, 1, 0); PG8_LDB(B1, 1, 1); PG8_SCHED; PG8_LDA(At, 1, 0); PG8_STAGE(PG8_SA(0, 1), a2 + hstep, voffA);
;             PG8_WAIT_V(8); PG8_WAIT_L(0); PG8_BAR; PG8_MMA(0, 0, At, B0); PG8_MMA(0, 1, At, B1); PG8_BAR; PG8_SCHED;
	s_setprio 1
	s_waitcnt lgkmcnt(0)
	v_mfma_f32_16x16x32_bf16 v[60:63], v[154:157], v[202:205], v[60:63]
	v_mfma_f32_16x16x32_bf16 v[56:59], v[162:165], v[202:205], v[56:59]
	v_mfma_f32_16x16x32_bf16 v[44:47], v[154:157], v[210:213], v[44:47]
	v_mfma_f32_16x16x32_bf16 v[40:43], v[162:165], v[210:213], v[40:43]
	v_mfma_f32_16x16x32_bf16 v[28:31], v[154:157], v[218:221], v[28:31]
	v_mfma_f32_16x16x32_bf16 v[24:27], v[162:165], v[218:221], v[24:27]
	v_mfma_f32_16x16x32_bf16 v[12:15], v[154:157], v[226:229], v[12:15]
	v_mfma_f32_16x16x32_bf16 v[8:11], v[162:165], v[226:229], v[8:11]
	v_mfma_f32_16x16x32_bf16 v[60:63], v[158:161], v[206:209], v[60:63]
	v_mfma_f32_16x16x32_bf16 v[56:59], v[172:175], v[206:209], v[56:59]
	v_mfma_f32_16x16x32_bf16 v[44:47], v[158:161], v[214:217], v[44:47]
	v_mfma_f32_16x16x32_bf16 v[40:43], v[172:175], v[214:217], v[40:43]
	v_mfma_f32_16x16x32_bf16 v[28:31], v[158:161], v[222:225], v[28:31]
	v_mfma_f32_16x16x32_bf16 v[24:27], v[172:175], v[222:225], v[24:27]
	v_mfma_f32_16x16x32_bf16 v[12:15], v[158:161], v[230:233], v[12:15]
	v_mfma_f32_16x16x32_bf16 v[8:11], v[172:175], v[230:233], v[8:11]
	s_setprio 0
	s_setprio 1
	v_mfma_f32_16x16x32_bf16 v[52:55], v[176:179], v[202:205], v[52:55]
	v_mfma_f32_16x16x32_bf16 v[48:51], v[184:187], v[202:205], v[48:51]
	v_mfma_f32_16x16x32_bf16 v[36:39], v[176:179], v[210:213], v[36:39]
	v_mfma_f32_16x16x32_bf16 v[32:35], v[184:187], v[210:213], v[32:35]
	v_mfma_f32_16x16x32_bf16 v[20:23], v[176:179], v[218:221], v[20:23]
	v_mfma_f32_16x16x32_bf16 v[16:19], v[184:187], v[218:221], v[16:19]
	v_mfma_f32_16x16x32_bf16 v[4:7], v[176:179], v[226:229], v[4:7]
	v_mfma_f32_16x16x32_bf16 v[0:3], v[184:187], v[226:229], v[0:3]
	v_mfma_f32_16x16x32_bf16 v[52:55], v[180:183], v[206:209], v[52:55]
	v_mfma_f32_16x16x32_bf16 v[48:51], v[188:191], v[206:209], v[48:51]
	v_mfma_f32_16x16x32_bf16 v[36:39], v[180:183], v[214:217], v[36:39]
	v_mfma_f32_16x16x32_bf16 v[32:35], v[188:191], v[214:217], v[32:35]
	v_mfma_f32_16x16x32_bf16 v[20:23], v[180:183], v[222:225], v[20:23]
	v_mfma_f32_16x16x32_bf16 v[16:19], v[188:191], v[222:225], v[16:19]
	v_mfma_f32_16x16x32_bf16 v[4:7], v[180:183], v[230:233], v[4:7]
	v_mfma_f32_16x16x32_bf16 v[0:3], v[188:191], v[230:233], v[0:3]
	s_setprio 0
	s_barrier
	s_add_i32 s52, 0, 0x18000
	v_add_u32_e32 v153, s52, v147
	s_add_i32 s53, 0, 0x1c000
	ds_read_b128 v[154:157], v153
	ds_read_b128 v[158:161], v153 offset:1024
	ds_read_b128 v[162:165], v153 offset:2048
	ds_read_b128 v[172:175], v153 offset:3072
	v_add_u32_e32 v153, s53, v147
	ds_read_b128 v[176:179], v153
	ds_read_b128 v[180:183], v153 offset:1024
	ds_read_b128 v[184:187], v153 offset:2048
	ds_read_b128 v[188:191], v153 offset:3072
	s_add_u32 s30, s30, 0x40000
	s_addc_u32 s31, s31, 0
	s_mov_b32 m0, s38
	v_lshl_add_u64 v[234:235], s[30:31], 0, v[134:135]
	ds_read_b128 v[202:205], v152 offset:32768
	ds_read_b128 v[206:209], v152 offset:33792
	ds_read_b128 v[210:213], v152 offset:34816
	ds_read_b128 v[214:217], v152 offset:35840
	ds_read_b128 v[218:221], v152 offset:36864
	ds_read_b128 v[222:225], v152 offset:37888
	ds_read_b128 v[226:229], v152 offset:38912
	ds_read_b128 v[230:233], v152 offset:39936
	global_load_lds_dwordx4 v[234:235], off
	v_lshl_add_u64 v[234:235], s[30:31], 0, v[130:131]
	s_mov_b32 m0, s39
	s_nop 0
	global_load_lds_dwordx4 v[234:235], off
	s_waitcnt vmcnt(8)
	s_waitcnt lgkmcnt(0)
	s_barrier
	s_setprio 1
	s_waitcnt lgkmcnt(0)
	v_mfma_f32_16x16x32_bf16 v[124:127], v[154:157], v[202:205], v[124:127]
	v_mfma_f32_16x16x32_bf16 v[120:123], v[162:165], v[202:205], v[120:123]
	v_mfma_f32_16x16x32_bf16 v[108:111], v[154:157], v[210:213], v[108:111]
	v_mfma_f32_16x16x32_bf16 v[104:107], v[162:165], v[210:213], v[104:107]
	v_mfma_f32_16x16x32_bf16 v[92:95], v[154:157], v[218:221], v[92:95]
	v_mfma_f32_16x16x32_bf16 v[88:91], v[162:165], v[218:221], v[88:91]
	v_mfma_f32_16x16x32_bf16 v[76:79], v[154:157], v[226:229], v[76:79]
	v_mfma_f32_16x16x32_bf16 v[72:75], v[162:165], v[226:229], v[72:75]
	v_mfma_f32_16x16x32_bf16 v[124:127], v[158:161], v[206:209], v[124:127]
	v_mfma_f32_16x16x32_bf16 v[120:123], v[172:175], v[206:209], v[120:123]
	v_mfma_f32_16x16x32_bf16 v[108:111], v[158:161], v[214:217], v[108:111]
	v_mfma_f32_16x16x32_bf16 v[104:107], v[172:175], v[214:217], v[104:107]
	v_mfma_f32_16x16x32_bf16 v[92:95], v[158:161], v[222:225], v[92:95]
	v_mfma_f32_16x16x32_bf16 v[88:91], v[172:175], v[222:225], v[88:91]
	v_mfma_f32_16x16x32_bf16 v[76:79], v[158:161], v[230:233], v[76:79]
	v_mfma_f32_16x16x32_bf16 v[72:75], v[172:175], v[230:233], v[72:75]
	s_setprio 0
	s_setprio 1
	v_mfma_f32_16x16x32_bf16 v[116:119], v[176:179], v[202:205], v[116:119]
	v_mfma_f32_16x16x32_bf16 v[112:115], v[184:187], v[202:205], v[112:115]
	v_mfma_f32_16x16x32_bf16 v[100:103], v[176:179], v[210:213], v[100:103]
	v_mfma_f32_16x16x32_bf16 v[96:99], v[184:187], v[210:213], v[96:99]
	v_mfma_f32_16x16x32_bf16 v[84:87], v[176:179], v[218:221], v[84:87]
	v_mfma_f32_16x16x32_bf16 v[80:83], v[184:187], v[218:221], v[80:83]
	v_mfma_f32_16x16x32_bf16 v[68:71], v[176:179], v[226:229], v[68:71]
	v_mfma_f32_16x16x32_bf16 v[64:67], v[184:187], v[226:229], v[64:67]
	v_mfma_f32_16x16x32_bf16 v[116:119], v[180:183], v[206:209], v[116:119]
	v_mfma_f32_16x16x32_bf16 v[112:115], v[188:191], v[206:209], v[112:115]
	v_mfma_f32_16x16x32_bf16 v[100:103], v[180:183], v[214:217], v[100:103]
	v_mfma_f32_16x16x32_bf16 v[96:99], v[188:191], v[214:217], v[96:99]
	v_mfma_f32_16x16x32_bf16 v[84:87], v[180:183], v[222:225], v[84:87]
	v_mfma_f32_16x16x32_bf16 v[80:83], v[188:191], v[222:225], v[80:83]
	v_mfma_f32_16x16x32_bf16 v[68:71], v[180:183], v[230:233], v[68:71]
	v_mfma_f32_16x16x32_bf16 v[64:67], v[188:191], v[230:233], v[64:67]
	s_setprio 0
	s_barrier
; #define PG8_STAGE(bufoff, gbase, voff) do { _Pragma("unroll") for (int _i = 0; _i < 2; ++_i) \
;         __builtin_amdgcn_global_load_lds((const unsigned*)((const char*)(gbase) + (voff)[_i]), (PG8_LAS unsigned*)(lds + (bufoff) + ldsw + _i * 8192), 16, 0, 0); } while (0)
; #define PG8_LDA(dst, b, h) do { _Pragma("unroll") for (int m = 0; m < 4; ++m) _Pragma("unroll") for (int k = 0; k < 2; ++k) dst[m][k] = *(const PG8_LAS bf16x8*)(lds + PG8_SA(b, h) + aoff + m * 2048 + k * 1024); } while (0)
; #define PG8_MMA(ai, bj, At, Bt) do { __builtin_amdgcn_s_setprio(1); _Pragma("unroll") for (int m = 0; m < 4; ++m) _Pragma("unroll") for (int n = 0; n < 2; ++n) _Pragma("unroll") for (int k = 0; k < 2; ++k) \
;         acc[ai][bj][m][n] = __builtin_amdgcn_mfma_f32_16x16x32_bf16(Bt[n][k], At[m][k], acc[ai][bj][m][n], 0, 0, 0); __builtin_amdgcn_s_setprio(0); } while (0)
; #define PG8_WAIT_V(n) asm volatile("s_waitcnt vmcnt(" #n ")" ::: "memory")
; #define PG8_WAIT_L(n) asm volatile("s_waitcnt lgkmcnt(" #n ")" ::: "memory")
; #define PG8_BAR __builtin_amdgcn_s_barrier()
; #define PG8_SCHED __builtin_amdgcn_sched_barrier(0)
; template <class Epi, class Sched, bool ALIGN_EPI = false, bool SP2 = false>
; __device__ __forceinline__ void gemm_phase(PG8_LAS unsigned char* lds, const Gemm g, const Sched& S, const Epi& E) {
;     ...
;             PG8_LDA(At, 1, 1); PG8_STAGE(PG8_SB(1, 0), b3, voffB); PG8_STAGE(PG8_SB(1, 1), b3 + hstep, voffB); PG8_STAGE(PG8_SA(1, 0), a3, voffA);
;             PG8_WAIT_V(8); PG8_WAIT_L(0); PG8_BAR; PG8_MMA(1, 0, At, B0); PG8_MMA(1, 1, At, B1); PG8_BAR; PG8_SCHED;
	s_setprio 2
	s_add_i32 s30, s52, s34
	v_lshl_add_u64 v[144:145], v[144:145], 0, s[10:11]
	s_mov_b32 m0, s30
	ds_read_b128 v[202:205], v152 offset:49152
	ds_read_b128 v[206:209], v152 offset:50176
	ds_read_b128 v[210:213], v152 offset:51200
	ds_read_b128 v[214:217], v152 offset:52224
	ds_read_b128 v[218:221], v152 offset:53248
	ds_read_b128 v[222:225], v152 offset:54272
	ds_read_b128 v[226:229], v152 offset:55296
	ds_read_b128 v[230:233], v152 offset:56320
	global_load_lds_dwordx4 v[144:145], off
	s_add_i32 m0, s30, 0x2000
	s_add_u32 s28, s28, 0x40080
	v_lshl_add_u64 v[144:145], v[166:167], 0, s[10:11]
	s_addc_u32 s29, s29, 0
	s_add_i32 s30, s53, s34
	global_load_lds_dwordx4 v[144:145], off
	v_lshl_add_u64 v[144:145], s[28:29], 0, v[132:133]
	s_mov_b32 m0, s30
	s_nop 0
	global_load_lds_dwordx4 v[144:145], off
	v_lshl_add_u64 v[144:145], s[28:29], 0, v[128:129]
	s_add_i32 m0, s30, 0x2000
	s_nop 0
	global_load_lds_dwordx4 v[144:145], off
	v_lshl_add_u64 v[144:145], v[192:193], 0, s[10:11]
	s_mov_b32 m0, s41
	s_nop 0
	global_load_lds_dwordx4 v[144:145], off
	v_lshl_add_u64 v[144:145], v[196:197], 0, s[10:11]
	s_mov_b32 m0, s42
	s_nop 0
	global_load_lds_dwordx4 v[144:145], off
	s_waitcnt vmcnt(8)
	s_waitcnt lgkmcnt(0)
	s_barrier
	s_setprio 1
	s_waitcnt lgkmcnt(0)
	v_mfma_f32_16x16x32_bf16 v[60:63], v[154:157], v[202:205], v[60:63]
	v_mfma_f32_16x16x32_bf16 v[56:59], v[162:165], v[202:205], v[56:59]
	v_mfma_f32_16x16x32_bf16 v[44:47], v[154:157], v[210:213], v[44:47]
	v_mfma_f32_16x16x32_bf16 v[40:43], v[162:165], v[210:213], v[40:43]
	v_mfma_f32_16x16x32_bf16 v[28:31], v[154:157], v[218:221], v[28:31]
	v_mfma_f32_16x16x32_bf16 v[24:27], v[162:165], v[218:221], v[24:27]
	v_mfma_f32_16x16x32_bf16 v[12:15], v[154:157], v[226:229], v[12:15]
	v_mfma_f32_16x16x32_bf16 v[8:11], v[162:165], v[226:229], v[8:11]
	v_mfma_f32_16x16x32_bf16 v[60:63], v[158:161], v[206:209], v[60:63]
	v_mfma_f32_16x16x32_bf16 v[56:59], v[172:175], v[206:209], v[56:59]
	v_mfma_f32_16x16x32_bf16 v[44:47], v[158:161], v[214:217], v[44:47]
	v_mfma_f32_16x16x32_bf16 v[40:43], v[172:175], v[214:217], v[40:43]
	v_mfma_f32_16x16x32_bf16 v[28:31], v[158:161], v[222:225], v[28:31]
	v_mfma_f32_16x16x32_bf16 v[24:27], v[172:175], v[222:225], v[24:27]
	v_mfma_f32_16x16x32_bf16 v[12:15], v[158:161], v[230:233], v[12:15]
	v_mfma_f32_16x16x32_bf16 v[8:11], v[172:175], v[230:233], v[8:11]
	s_setprio 0
	s_setprio 1
	v_mfma_f32_16x16x32_bf16 v[52:55], v[176:179], v[202:205], v[52:55]
	v_mfma_f32_16x16x32_bf16 v[48:51], v[184:187], v[202:205], v[48:51]
	v_mfma_f32_16x16x32_bf16 v[36:39], v[176:179], v[210:213], v[36:39]
	v_mfma_f32_16x16x32_bf16 v[32:35], v[184:187], v[210:213], v[32:35]
	v_mfma_f32_16x16x32_bf16 v[20:23], v[176:179], v[218:221], v[20:23]
	v_mfma_f32_16x16x32_bf16 v[16:19], v[184:187], v[218:221], v[16:19]
	v_mfma_f32_16x16x32_bf16 v[4:7], v[176:179], v[226:229], v[4:7]
	v_mfma_f32_16x16x32_bf16 v[0:3], v[184:187], v[226:229], v[0:3]
	v_mfma_f32_16x16x32_bf16 v[52:55], v[180:183], v[206:209], v[52:55]
	v_mfma_f32_16x16x32_bf16 v[48:51], v[188:191], v[206:209], v[48:51]
	v_mfma_f32_16x16x32_bf16 v[36:39], v[180:183], v[214:217], v[36:39]
	v_mfma_f32_16x16x32_bf16 v[32:35], v[188:191], v[214:217], v[32:35]
	v_mfma_f32_16x16x32_bf16 v[20:23], v[180:183], v[222:225], v[20:23]
	v_mfma_f32_16x16x32_bf16 v[16:19], v[188:191], v[222:225], v[16:19]
	v_mfma_f32_16x16x32_bf16 v[4:7], v[180:183], v[230:233], v[4:7]
	v_mfma_f32_16x16x32_bf16 v[0:3], v[188:191], v[230:233], v[0:3]
	s_setprio 0
	s_barrier
	s_add_i32 s51, s51, 2
	s_add_u32 s0, s0, 0x100
	s_addc_u32 s1, s1, 0
	s_add_u32 s49, s49, 0x100
	s_addc_u32 s50, s50, 0
	s_cmp_gt_u32 s51, 13
	s_cbranch_scc0 .LBB0_150
	s_and_b64 vcc, exec, s[12:13]
	s_cbranch_vccz .LBB0_153
	s_barrier

; #define PG8_STAGE(bufoff, gbase, voff) do { _Pragma("unroll") for (int _i = 0; _i < 2; ++_i) \
;         __builtin_amdgcn_global_load_lds((const unsigned*)((const char*)(gbase) + (voff)[_i]), (PG8_LAS unsigned*)(lds + (bufoff) + ldsw + _i * 8192), 16, 0, 0); } while (0)
; #define PG8_LDA(dst, b, h) do { _Pragma("unroll") for (int m = 0; m < 4; ++m) _Pragma("unroll") for (int k = 0; k < 2; ++k) dst[m][k] = *(const PG8_LAS bf16x8*)(lds + PG8_SA(b, h) + aoff + m * 2048 + k * 1024); } while (0)
; #define PG8_LDB(dst, b, h) do { _Pragma("unroll") for (int n = 0; n < 2; ++n) _Pragma("unroll") for (int k = 0; k < 2; ++k) dst[n][k] = *(const PG8_LAS bf16x8*)(lds + PG8_SB(b, h) + boff + n * 2048 + k * 1024); } while (0)
; #define PG8_MMA(ai, bj, At, Bt) do { __builtin_amdgcn_s_setprio(1); _Pragma("unroll") for (int m = 0; m < 4; ++m) _Pragma("unroll") for (int n = 0; n < 2; ++n) _Pragma("unroll") for (int k = 0; k < 2; ++k) \
;         acc[ai][bj][m][n] = __builtin_amdgcn_mfma_f32_16x16x32_bf16(Bt[n][k], At[m][k], acc[ai][bj][m][n], 0, 0, 0); __builtin_amdgcn_s_setprio(0); } while (0)
; #define PG8_WAIT_V(n) asm volatile("s_waitcnt vmcnt(" #n ")" ::: "memory")
; #define PG8_WAIT_L(n) asm volatile("s_waitcnt lgkmcnt(" #n ")" ::: "memory")
; #define PG8_BAR __builtin_amdgcn_s_barrier()
; #define PG8_SCHED __builtin_amdgcn_sched_barrier(0)
; template <class Epi, class Sched, bool ALIGN_EPI = false, bool SP2 = false>
; __device__ __forceinline__ void gemm_phase(PG8_LAS unsigned char* lds, const Gemm g, const Sched& S, const Epi& E) {
;     ...
;             const bool last = (t == nt - 2);
;             const char* a1 = cA + (size_t)(t + 1) * kstep;
;             const char* a2 = last ? nA : cA + (size_t)(t + 2) * kstep; const char* b2 = last ? nB : cB + (size_t)(t + 2) * kstep;
;             const char* a3 = a2 + kstep; const char* b3 = b2 + kstep;
;             if (last && has_next) S.a_ready(nxt);
;             if constexpr (SP2) {
;             PG8_LDB(B0, 0, 0); PG8_LDB(B1, 0, 1); PG8_SCHED; PG8_LDA(At, 0, 0); PG8_STAGE(PG8_SA(1, 1), a1 + hstep, voffA);
;             PG8_WAIT_V(8); PG8_WAIT_L(0); PG8_BAR; PG8_MMA(0, 0, At, B0); PG8_MMA(0, 1, At, B1); PG8_BAR; PG8_SCHED;
;             PG8_LDA(At, 0, 1); PG8_STAGE(PG8_SB(0, 0), b2, voffB); PG8_STAGE(PG8_SB(0, 1), b2 + hstep, voffB); PG8_STAGE(PG8_SA(0, 0), a2, voffA);
.LBB0_232:
	ds_read_b128 v[128:131], v218
	ds_read_b128 v[132:135], v218 offset:1024
	ds_read_b128 v[136:139], v218 offset:2048
	ds_read_b128 v[140:143], v218 offset:3072
	ds_read_b128 v[144:147], v219
	ds_read_b128 v[148:151], v219 offset:1024
	ds_read_b128 v[152:155], v219 offset:2048
	ds_read_b128 v[156:159], v219 offset:3072
	s_add_u32 s30, s0, 0x100
	s_addc_u32 s31, s1, 0
	s_cmp_eq_u32 s55, 40
	s_cselect_b32 s37, s13, s31
	s_cselect_b32 s36, s12, s30
	s_cselect_b32 s35, s29, s54
	s_cselect_b32 s34, s28, s33
	v_lshl_add_u64 v[192:193], s[0:1], 0, v[182:183]
	s_add_i32 m0, s39, 0xc000
	ds_read_b128 v[160:163], v220
	ds_read_b128 v[164:167], v220 offset:1024
	ds_read_b128 v[188:191], v220 offset:2048
	ds_read_b128 v[226:229], v220 offset:3072
	ds_read_b128 v[230:233], v220 offset:4096
	ds_read_b128 v[234:237], v220 offset:5120
	ds_read_b128 v[238:241], v220 offset:6144
	ds_read_b128 v[242:245], v220 offset:7168
	global_load_lds_dwordx4 v[192:193], off
	v_lshl_add_u64 v[192:193], s[0:1], 0, v[184:185]
	s_add_i32 m0, s39, 0xe000
	s_nop 0
	global_load_lds_dwordx4 v[192:193], off
	s_waitcnt vmcnt(8)
	s_waitcnt lgkmcnt(0)
	s_barrier
	s_setprio 1
	s_waitcnt lgkmcnt(0)
	v_mfma_f32_16x16x32_bf16 v[124:127], v[128:131], v[160:163], v[124:127]
	v_mfma_f32_16x16x32_bf16 v[120:123], v[136:139], v[160:163], v[120:123]
	v_mfma_f32_16x16x32_bf16 v[108:111], v[128:131], v[188:191], v[108:111]
	v_mfma_f32_16x16x32_bf16 v[104:107], v[136:139], v[188:191], v[104:107]
	v_mfma_f32_16x16x32_bf16 v[92:95], v[128:131], v[230:233], v[92:95]
	v_mfma_f32_16x16x32_bf16 v[88:91], v[136:139], v[230:233], v[88:91]
	v_mfma_f32_16x16x32_bf16 v[76:79], v[128:131], v[238:241], v[76:79]
	v_mfma_f32_16x16x32_bf16 v[72:75], v[136:139], v[238:241], v[72:75]
	v_mfma_f32_16x16x32_bf16 v[124:127], v[132:135], v[164:167], v[124:127]
	v_mfma_f32_16x16x32_bf16 v[120:123], v[140:143], v[164:167], v[120:123]
	v_mfma_f32_16x16x32_bf16 v[108:111], v[132:135], v[226:229], v[108:111]
	v_mfma_f32_16x16x32_bf16 v[104:107], v[140:143], v[226:229], v[104:107]
	v_mfma_f32_16x16x32_bf16 v[92:95], v[132:135], v[234:237], v[92:95]
	v_mfma_f32_16x16x32_bf16 v[88:91], v[140:143], v[234:237], v[88:91]
	v_mfma_f32_16x16x32_bf16 v[76:79], v[132:135], v[242:245], v[76:79]
	v_mfma_f32_16x16x32_bf16 v[72:75], v[140:143], v[242:245], v[72:75]
	s_setprio 0
	s_setprio 1
	v_mfma_f32_16x16x32_bf16 v[116:119], v[144:147], v[160:163], v[116:119]
	v_mfma_f32_16x16x32_bf16 v[112:115], v[152:155], v[160:163], v[112:115]
	v_mfma_f32_16x16x32_bf16 v[100:103], v[144:147], v[188:191], v[100:103]
	v_mfma_f32_16x16x32_bf16 v[96:99], v[152:155], v[188:191], v[96:99]
	v_mfma_f32_16x16x32_bf16 v[84:87], v[144:147], v[230:233], v[84:87]
	v_mfma_f32_16x16x32_bf16 v[80:83], v[152:155], v[230:233], v[80:83]
	v_mfma_f32_16x16x32_bf16 v[68:71], v[144:147], v[238:241], v[68:71]
	v_mfma_f32_16x16x32_bf16 v[64:67], v[152:155], v[238:241], v[64:67]
	v_mfma_f32_16x16x32_bf16 v[116:119], v[148:151], v[164:167], v[116:119]
	v_mfma_f32_16x16x32_bf16 v[112:115], v[156:159], v[164:167], v[112:115]
	v_mfma_f32_16x16x32_bf16 v[100:103], v[148:151], v[226:229], v[100:103]
	v_mfma_f32_16x16x32_bf16 v[96:99], v[156:159], v[226:229], v[96:99]
	v_mfma_f32_16x16x32_bf16 v[84:87], v[148:151], v[234:237], v[84:87]
	v_mfma_f32_16x16x32_bf16 v[80:83], v[156:159], v[234:237], v[80:83]
	v_mfma_f32_16x16x32_bf16 v[68:71], v[148:151], v[242:245], v[68:71]
	v_mfma_f32_16x16x32_bf16 v[64:67], v[156:159], v[242:245], v[64:67]
	s_setprio 0
	s_barrier
	s_setprio 2
	s_add_i32 s0, s48, s38
	v_lshl_add_u64 v[192:193], s[34:35], 0, v[174:175]
	s_mov_b32 m0, s0
	ds_read_b128 v[160:163], v220 offset:16384
	ds_read_b128 v[164:167], v220 offset:17408
	ds_read_b128 v[188:191], v220 offset:18432
	ds_read_b128 v[226:229], v220 offset:19456
	ds_read_b128 v[230:233], v220 offset:20480
	ds_read_b128 v[234:237], v220 offset:21504
	ds_read_b128 v[238:241], v220 offset:22528
	ds_read_b128 v[242:245], v220 offset:23552
	global_load_lds_dwordx4 v[192:193], off
	s_add_i32 m0, s0, 0x2000
	s_add_u32 s0, s34, 0xb0000
	v_lshl_add_u64 v[246:247], s[34:35], 0, v[178:179]
	s_addc_u32 s1, s35, 0
	s_add_i32 s56, s49, s38
	global_load_lds_dwordx4 v[246:247], off
	v_lshl_add_u64 v[248:249], s[0:1], 0, v[174:175]
	s_mov_b32 m0, s56
	v_lshl_add_u64 v[250:251], s[36:37], 0, v[176:177]
	global_load_lds_dwordx4 v[248:249], off
	v_lshl_add_u64 v[248:249], s[0:1], 0, v[178:179]
	s_add_i32 m0, s56, 0x2000
	s_nop 0
	global_load_lds_dwordx4 v[248:249], off
	v_lshl_add_u64 v[248:249], s[36:37], 0, v[172:173]
	s_mov_b32 m0, s39
	s_nop 0
	global_load_lds_dwordx4 v[248:249], off
	s_mov_b32 m0, s40
	s_nop 0
	global_load_lds_dwordx4 v[250:251], off
	s_waitcnt vmcnt(8)
	s_waitcnt lgkmcnt(0)
	s_barrier
; #define PG8_STAGE(bufoff, gbase, voff) do { _Pragma("unroll") for (int _i = 0; _i < 2; ++_i) \
;         __builtin_amdgcn_global_load_lds((const unsigned*)((const char*)(gbase) + (voff)[_i]), (PG8_LAS unsigned*)(lds + (bufoff) + ldsw + _i * 8192), 16, 0, 0); } while (0)
; #define PG8_LDA(dst, b, h) do { _Pragma("unroll") for (int m = 0; m < 4; ++m) _Pragma("unroll") for (int k = 0; k < 2; ++k) dst[m][k] = *(const PG8_LAS bf16x8*)(lds + PG8_SA(b, h) + aoff + m * 2048 + k * 1024); } while (0)
; #define PG8_LDB(dst, b, h) do { _Pragma("unroll") for (int n = 0; n < 2; ++n) _Pragma("unroll") for (int k = 0; k < 2; ++k) dst[n][k] = *(const PG8_LAS bf16x8*)(lds + PG8_SB(b, h) + boff + n * 2048 + k * 1024); } while (0)
; #define PG8_MMA(ai, bj, At, Bt) do { __builtin_amdgcn_s_setprio(1); _Pragma("unroll") for (int m = 0; m < 4; ++m) _Pragma("unroll") for (int n = 0; n < 2; ++n) _Pragma("unroll") for (int k = 0; k < 2; ++k) \
;         acc[ai][bj][m][n] = __builtin_amdgcn_mfma_f32_16x16x32_bf16(Bt[n][k], At[m][k], acc[ai][bj][m][n], 0, 0, 0); __builtin_amdgcn_s_setprio(0); } while (0)
; #define PG8_WAIT_V(n) asm volatile("s_waitcnt vmcnt(" #n ")" ::: "memory")
; #define PG8_WAIT_L(n) asm volatile("s_waitcnt lgkmcnt(" #n ")" ::: "memory")
; #define PG8_BAR __builtin_amdgcn_s_barrier()
; #define PG8_SCHED __builtin_amdgcn_sched_barrier(0)
; template <class Epi, class Sched, bool ALIGN_EPI = false, bool SP2 = false>
; __device__ __forceinline__ void gemm_phase(PG8_LAS unsigned char* lds, const Gemm g, const Sched& S, const Epi& E) {
;     ...
;             PG8_WAIT_V(8); PG8_WAIT_L(0); PG8_BAR; PG8_MMA(1, 0, At, B0); PG8_MMA(1, 1, At, B1); PG8_BAR; PG8_SCHED;
;             PG8_LDB(B0, 1, 0); PG8_LDB(B1, 1, 1); PG8_SCHED; PG8_LDA(At, 1, 0); PG8_STAGE(PG8_SA(0, 1), a2 + hstep, voffA);
;             PG8_WAIT_V(8); PG8_WAIT_L(0); PG8_BAR; PG8_MMA(0, 0, At, B0); PG8_MMA(0, 1, At, B1); PG8_BAR; PG8_SCHED;
	s_setprio 1
	s_waitcnt lgkmcnt(0)
	v_mfma_f32_16x16x32_bf16 v[60:63], v[128:131], v[160:163], v[60:63]
	v_mfma_f32_16x16x32_bf16 v[56:59], v[136:139], v[160:163], v[56:59]
	v_mfma_f32_16x16x32_bf16 v[44:47], v[128:131], v[188:191], v[44:47]
	v_mfma_f32_16x16x32_bf16 v[40:43], v[136:139], v[188:191], v[40:43]
	v_mfma_f32_16x16x32_bf16 v[28:31], v[128:131], v[230:233], v[28:31]
	v_mfma_f32_16x16x32_bf16 v[24:27], v[136:139], v[230:233], v[24:27]
	v_mfma_f32_16x16x32_bf16 v[12:15], v[128:131], v[238:241], v[12:15]
	v_mfma_f32_16x16x32_bf16 v[8:11], v[136:139], v[238:241], v[8:11]
	v_mfma_f32_16x16x32_bf16 v[60:63], v[132:135], v[164:167], v[60:63]
	v_mfma_f32_16x16x32_bf16 v[56:59], v[140:143], v[164:167], v[56:59]
	v_mfma_f32_16x16x32_bf16 v[44:47], v[132:135], v[226:229], v[44:47]
	v_mfma_f32_16x16x32_bf16 v[40:43], v[140:143], v[226:229], v[40:43]
	v_mfma_f32_16x16x32_bf16 v[28:31], v[132:135], v[234:237], v[28:31]
	v_mfma_f32_16x16x32_bf16 v[24:27], v[140:143], v[234:237], v[24:27]
	v_mfma_f32_16x16x32_bf16 v[12:15], v[132:135], v[242:245], v[12:15]
	v_mfma_f32_16x16x32_bf16 v[8:11], v[140:143], v[242:245], v[8:11]
	s_setprio 0
	s_setprio 1
	v_mfma_f32_16x16x32_bf16 v[52:55], v[144:147], v[160:163], v[52:55]
	v_mfma_f32_16x16x32_bf16 v[48:51], v[152:155], v[160:163], v[48:51]
	v_mfma_f32_16x16x32_bf16 v[36:39], v[144:147], v[188:191], v[36:39]
	v_mfma_f32_16x16x32_bf16 v[32:35], v[152:155], v[188:191], v[32:35]
	v_mfma_f32_16x16x32_bf16 v[20:23], v[144:147], v[230:233], v[20:23]
	v_mfma_f32_16x16x32_bf16 v[16:19], v[152:155], v[230:233], v[16:19]
	v_mfma_f32_16x16x32_bf16 v[4:7], v[144:147], v[238:241], v[4:7]
	v_mfma_f32_16x16x32_bf16 v[0:3], v[152:155], v[238:241], v[0:3]
	v_mfma_f32_16x16x32_bf16 v[52:55], v[148:151], v[164:167], v[52:55]
	v_mfma_f32_16x16x32_bf16 v[48:51], v[156:159], v[164:167], v[48:51]
	v_mfma_f32_16x16x32_bf16 v[36:39], v[148:151], v[226:229], v[36:39]
	v_mfma_f32_16x16x32_bf16 v[32:35], v[156:159], v[226:229], v[32:35]
	v_mfma_f32_16x16x32_bf16 v[20:23], v[148:151], v[234:237], v[20:23]
	v_mfma_f32_16x16x32_bf16 v[16:19], v[156:159], v[234:237], v[16:19]
	v_mfma_f32_16x16x32_bf16 v[4:7], v[148:151], v[242:245], v[4:7]
	v_mfma_f32_16x16x32_bf16 v[0:3], v[156:159], v[242:245], v[0:3]
	s_setprio 0
	s_barrier
	s_add_i32 s56, 0, 0x18000
	s_add_i32 s57, 0, 0x1c000
	v_add_u32_e32 v140, s56, v196
	v_add_u32_e32 v156, s57, v196
	ds_read_b128 v[128:131], v140
	ds_read_b128 v[132:135], v140 offset:1024
	ds_read_b128 v[136:139], v140 offset:2048
	ds_read_b128 v[140:143], v140 offset:3072
	ds_read_b128 v[144:147], v156
	ds_read_b128 v[148:151], v156 offset:1024
	ds_read_b128 v[152:155], v156 offset:2048
	ds_read_b128 v[156:159], v156 offset:3072
	s_add_u32 s0, s36, 0xb0000
	s_addc_u32 s1, s37, 0
	s_mov_b32 m0, s41
	v_lshl_add_u64 v[252:253], s[0:1], 0, v[172:173]
	ds_read_b128 v[160:163], v220 offset:32768
	ds_read_b128 v[164:167], v220 offset:33792
	ds_read_b128 v[188:191], v220 offset:34816
	ds_read_b128 v[226:229], v220 offset:35840
	ds_read_b128 v[230:233], v220 offset:36864
	ds_read_b128 v[234:237], v220 offset:37888
	ds_read_b128 v[238:241], v220 offset:38912
	ds_read_b128 v[242:245], v220 offset:39936
	global_load_lds_dwordx4 v[252:253], off
	v_lshl_add_u64 v[252:253], s[0:1], 0, v[176:177]
	s_mov_b32 m0, s42
	s_nop 0
	global_load_lds_dwordx4 v[252:253], off
	s_waitcnt vmcnt(8)
	s_waitcnt lgkmcnt(0)
	s_barrier
	s_setprio 1
	s_waitcnt lgkmcnt(0)
	v_mfma_f32_16x16x32_bf16 v[124:127], v[128:131], v[160:163], v[124:127]
	v_mfma_f32_16x16x32_bf16 v[120:123], v[136:139], v[160:163], v[120:123]
	v_mfma_f32_16x16x32_bf16 v[108:111], v[128:131], v[188:191], v[108:111]
	v_mfma_f32_16x16x32_bf16 v[104:107], v[136:139], v[188:191], v[104:107]
	v_mfma_f32_16x16x32_bf16 v[92:95], v[128:131], v[230:233], v[92:95]
	v_mfma_f32_16x16x32_bf16 v[88:91], v[136:139], v[230:233], v[88:91]
	v_mfma_f32_16x16x32_bf16 v[76:79], v[128:131], v[238:241], v[76:79]
	v_mfma_f32_16x16x32_bf16 v[72:75], v[136:139], v[238:241], v[72:75]
	v_mfma_f32_16x16x32_bf16 v[124:127], v[132:135], v[164:167], v[124:127]
	v_mfma_f32_16x16x32_bf16 v[120:123], v[140:143], v[164:167], v[120:123]
	v_mfma_f32_16x16x32_bf16 v[108:111], v[132:135], v[226:229], v[108:111]
	v_mfma_f32_16x16x32_bf16 v[104:107], v[140:143], v[226:229], v[104:107]
	v_mfma_f32_16x16x32_bf16 v[92:95], v[132:135], v[234:237], v[92:95]
	v_mfma_f32_16x16x32_bf16 v[88:91], v[140:143], v[234:237], v[88:91]
	v_mfma_f32_16x16x32_bf16 v[76:79], v[132:135], v[242:245], v[76:79]
	v_mfma_f32_16x16x32_bf16 v[72:75], v[140:143], v[242:245], v[72:75]
	s_setprio 0
	s_setprio 1
	v_mfma_f32_16x16x32_bf16 v[116:119], v[144:147], v[160:163], v[116:119]
	v_mfma_f32_16x16x32_bf16 v[112:115], v[152:155], v[160:163], v[112:115]
	v_mfma_f32_16x16x32_bf16 v[100:103], v[144:147], v[188:191], v[100:103]
	v_mfma_f32_16x16x32_bf16 v[96:99], v[152:155], v[188:191], v[96:99]
	v_mfma_f32_16x16x32_bf16 v[84:87], v[144:147], v[230:233], v[84:87]
	v_mfma_f32_16x16x32_bf16 v[80:83], v[152:155], v[230:233], v[80:83]
	v_mfma_f32_16x16x32_bf16 v[68:71], v[144:147], v[238:241], v[68:71]
	v_mfma_f32_16x16x32_bf16 v[64:67], v[152:155], v[238:241], v[64:67]
	v_mfma_f32_16x16x32_bf16 v[116:119], v[148:151], v[164:167], v[116:119]
	v_mfma_f32_16x16x32_bf16 v[112:115], v[156:159], v[164:167], v[112:115]
	v_mfma_f32_16x16x32_bf16 v[100:103], v[148:151], v[226:229], v[100:103]
	v_mfma_f32_16x16x32_bf16 v[96:99], v[156:159], v[226:229], v[96:99]
	v_mfma_f32_16x16x32_bf16 v[84:87], v[148:151], v[234:237], v[84:87]
	v_mfma_f32_16x16x32_bf16 v[80:83], v[156:159], v[234:237], v[80:83]
	v_mfma_f32_16x16x32_bf16 v[68:71], v[148:151], v[242:245], v[68:71]
	v_mfma_f32_16x16x32_bf16 v[64:67], v[156:159], v[242:245], v[64:67]
	s_setprio 0
	s_barrier
; #define PG8_STAGE(bufoff, gbase, voff) do { _Pragma("unroll") for (int _i = 0; _i < 2; ++_i) \
;         __builtin_amdgcn_global_load_lds((const unsigned*)((const char*)(gbase) + (voff)[_i]), (PG8_LAS unsigned*)(lds + (bufoff) + ldsw + _i * 8192), 16, 0, 0); } while (0)
; #define PG8_LDA(dst, b, h) do { _Pragma("unroll") for (int m = 0; m < 4; ++m) _Pragma("unroll") for (int k = 0; k < 2; ++k) dst[m][k] = *(const PG8_LAS bf16x8*)(lds + PG8_SA(b, h) + aoff + m * 2048 + k * 1024); } while (0)
; #define PG8_MMA(ai, bj, At, Bt) do { __builtin_amdgcn_s_setprio(1); _Pragma("unroll") for (int m = 0; m < 4; ++m) _Pragma("unroll") for (int n = 0; n < 2; ++n) _Pragma("unroll") for (int k = 0; k < 2; ++k) \
;         acc[ai][bj][m][n] = __builtin_amdgcn_mfma_f32_16x16x32_bf16(Bt[n][k], At[m][k], acc[ai][bj][m][n], 0, 0, 0); __builtin_amdgcn_s_setprio(0); } while (0)
; #define PG8_WAIT_V(n) asm volatile("s_waitcnt vmcnt(" #n ")" ::: "memory")
; #define PG8_WAIT_L(n) asm volatile("s_waitcnt lgkmcnt(" #n ")" ::: "memory")
; #define PG8_BAR __builtin_amdgcn_s_barrier()
; #define PG8_SCHED __builtin_amdgcn_sched_barrier(0)
; template <class Epi, class Sched, bool ALIGN_EPI = false, bool SP2 = false>
; __device__ __forceinline__ void gemm_phase(PG8_LAS unsigned char* lds, const Gemm g, const Sched& S, const Epi& E) {
;     ...
;             PG8_LDA(At, 1, 1); PG8_STAGE(PG8_SB(1, 0), b3, voffB); PG8_STAGE(PG8_SB(1, 1), b3 + hstep, voffB); PG8_STAGE(PG8_SA(1, 0), a3, voffA);
;             PG8_WAIT_V(8); PG8_WAIT_L(0); PG8_BAR; PG8_MMA(1, 0, At, B0); PG8_MMA(1, 1, At, B1); PG8_BAR; PG8_SCHED;
	s_setprio 2
	s_add_i32 s0, s56, s38
	v_lshl_add_u64 v[192:193], v[192:193], 0, s[22:23]
	s_mov_b32 m0, s0
	ds_read_b128 v[160:163], v220 offset:49152
	ds_read_b128 v[164:167], v220 offset:50176
	ds_read_b128 v[188:191], v220 offset:51200
	ds_read_b128 v[226:229], v220 offset:52224
	ds_read_b128 v[230:233], v220 offset:53248
	ds_read_b128 v[234:237], v220 offset:54272
	ds_read_b128 v[238:241], v220 offset:55296
	ds_read_b128 v[242:245], v220 offset:56320
	global_load_lds_dwordx4 v[192:193], off
	s_add_i32 m0, s0, 0x2000
	s_add_u32 s0, s34, 0xb0080
	v_lshl_add_u64 v[192:193], v[246:247], 0, s[22:23]
	s_addc_u32 s1, s35, 0
	s_add_i32 s34, s57, s38
	global_load_lds_dwordx4 v[192:193], off
	v_lshl_add_u64 v[192:193], s[0:1], 0, v[174:175]
	s_mov_b32 m0, s34
	s_nop 0
	global_load_lds_dwordx4 v[192:193], off
	v_lshl_add_u64 v[192:193], s[0:1], 0, v[178:179]
	s_add_i32 m0, s34, 0x2000
	s_nop 0
	global_load_lds_dwordx4 v[192:193], off
	v_lshl_add_u64 v[192:193], v[248:249], 0, s[22:23]
	s_mov_b32 m0, s44
	s_nop 0
	global_load_lds_dwordx4 v[192:193], off
	v_lshl_add_u64 v[192:193], v[250:251], 0, s[22:23]
	s_mov_b32 m0, s45
	s_nop 0
	global_load_lds_dwordx4 v[192:193], off
	s_waitcnt vmcnt(8)
	s_waitcnt lgkmcnt(0)
	s_barrier
	s_setprio 1
	s_waitcnt lgkmcnt(0)
	v_mfma_f32_16x16x32_bf16 v[60:63], v[128:131], v[160:163], v[60:63]
	v_mfma_f32_16x16x32_bf16 v[56:59], v[136:139], v[160:163], v[56:59]
	v_mfma_f32_16x16x32_bf16 v[44:47], v[128:131], v[188:191], v[44:47]
	v_mfma_f32_16x16x32_bf16 v[40:43], v[136:139], v[188:191], v[40:43]
	v_mfma_f32_16x16x32_bf16 v[28:31], v[128:131], v[230:233], v[28:31]
	v_mfma_f32_16x16x32_bf16 v[24:27], v[136:139], v[230:233], v[24:27]
	v_mfma_f32_16x16x32_bf16 v[12:15], v[128:131], v[238:241], v[12:15]
	v_mfma_f32_16x16x32_bf16 v[8:11], v[136:139], v[238:241], v[8:11]
	v_mfma_f32_16x16x32_bf16 v[60:63], v[132:135], v[164:167], v[60:63]
	v_mfma_f32_16x16x32_bf16 v[56:59], v[140:143], v[164:167], v[56:59]
	v_mfma_f32_16x16x32_bf16 v[44:47], v[132:135], v[226:229], v[44:47]
	v_mfma_f32_16x16x32_bf16 v[40:43], v[140:143], v[226:229], v[40:43]
	v_mfma_f32_16x16x32_bf16 v[28:31], v[132:135], v[234:237], v[28:31]
	v_mfma_f32_16x16x32_bf16 v[24:27], v[140:143], v[234:237], v[24:27]
	v_mfma_f32_16x16x32_bf16 v[12:15], v[132:135], v[242:245], v[12:15]
	v_mfma_f32_16x16x32_bf16 v[8:11], v[140:143], v[242:245], v[8:11]
	s_setprio 0
	s_setprio 1
	v_mfma_f32_16x16x32_bf16 v[52:55], v[144:147], v[160:163], v[52:55]
	v_mfma_f32_16x16x32_bf16 v[48:51], v[152:155], v[160:163], v[48:51]
	v_mfma_f32_16x16x32_bf16 v[36:39], v[144:147], v[188:191], v[36:39]
	v_mfma_f32_16x16x32_bf16 v[32:35], v[152:155], v[188:191], v[32:35]
	v_mfma_f32_16x16x32_bf16 v[20:23], v[144:147], v[230:233], v[20:23]
	v_mfma_f32_16x16x32_bf16 v[16:19], v[152:155], v[230:233], v[16:19]
	v_mfma_f32_16x16x32_bf16 v[4:7], v[144:147], v[238:241], v[4:7]
	v_mfma_f32_16x16x32_bf16 v[0:3], v[152:155], v[238:241], v[0:3]
	v_mfma_f32_16x16x32_bf16 v[52:55], v[148:151], v[164:167], v[52:55]
	v_mfma_f32_16x16x32_bf16 v[48:51], v[156:159], v[164:167], v[48:51]
	v_mfma_f32_16x16x32_bf16 v[36:39], v[148:151], v[226:229], v[36:39]
	v_mfma_f32_16x16x32_bf16 v[32:35], v[156:159], v[226:229], v[32:35]
	v_mfma_f32_16x16x32_bf16 v[20:23], v[148:151], v[234:237], v[20:23]
	v_mfma_f32_16x16x32_bf16 v[16:19], v[156:159], v[234:237], v[16:19]
	v_mfma_f32_16x16x32_bf16 v[4:7], v[148:151], v[242:245], v[4:7]
	v_mfma_f32_16x16x32_bf16 v[0:3], v[156:159], v[242:245], v[0:3]
	s_setprio 0
	s_barrier
	s_add_i32 s55, s55, 2
	s_add_u32 s33, s33, 0x100
	s_addc_u32 s54, s54, 0
	s_cmp_gt_u32 s55, 41
	s_mov_b64 s[0:1], s[30:31]
	s_cbranch_scc0 .LBB0_232
	s_and_b64 vcc, exec, s[24:25]
	s_cbranch_vccz .LBB0_235
	s_barrier

; #define PG8_STAGE(bufoff, gbase, voff) do { _Pragma("unroll") for (int _i = 0; _i < 2; ++_i) \
;         __builtin_amdgcn_global_load_lds((const unsigned*)((const char*)(gbase) + (voff)[_i]), (PG8_LAS unsigned*)(lds + (bufoff) + ldsw + _i * 8192), 16, 0, 0); } while (0)
; #define PG8_LDA(dst, b, h) do { _Pragma("unroll") for (int m = 0; m < 4; ++m) _Pragma("unroll") for (int k = 0; k < 2; ++k) dst[m][k] = *(const PG8_LAS bf16x8*)(lds + PG8_SA(b, h) + aoff + m * 2048 + k * 1024); } while (0)
; #define PG8_LDB(dst, b, h) do { _Pragma("unroll") for (int n = 0; n < 2; ++n) _Pragma("unroll") for (int k = 0; k < 2; ++k) dst[n][k] = *(const PG8_LAS bf16x8*)(lds + PG8_SB(b, h) + boff + n * 2048 + k * 1024); } while (0)
; #define PG8_MMA(ai, bj, At, Bt) do { __builtin_amdgcn_s_setprio(1); _Pragma("unroll") for (int m = 0; m < 4; ++m) _Pragma("unroll") for (int n = 0; n < 2; ++n) _Pragma("unroll") for (int k = 0; k < 2; ++k) \
;         acc[ai][bj][m][n] = __builtin_amdgcn_mfma_f32_16x16x32_bf16(Bt[n][k], At[m][k], acc[ai][bj][m][n], 0, 0, 0); __builtin_amdgcn_s_setprio(0); } while (0)
; #define PG8_WAIT_V(n) asm volatile("s_waitcnt vmcnt(" #n ")" ::: "memory")
; #define PG8_WAIT_L(n) asm volatile("s_waitcnt lgkmcnt(" #n ")" ::: "memory")
; #define PG8_BAR __builtin_amdgcn_s_barrier()
; #define PG8_SCHED __builtin_amdgcn_sched_barrier(0)
; template <class Epi, class Sched, bool ALIGN_EPI = false, bool SP2 = false>
; __device__ __forceinline__ void gemm_phase(PG8_LAS unsigned char* lds, const Gemm g, const Sched& S, const Epi& E) {
;     ...
;             const bool last = (t == nt - 2);
;             const char* a1 = cA + (size_t)(t + 1) * kstep;
;             const char* a2 = last ? nA : cA + (size_t)(t + 2) * kstep; const char* b2 = last ? nB : cB + (size_t)(t + 2) * kstep;
;             const char* a3 = a2 + kstep; const char* b3 = b2 + kstep;
;             if (last && has_next) S.a_ready(nxt);
;             if constexpr (SP2) {
;             PG8_LDB(B0, 0, 0); PG8_LDB(B1, 0, 1); PG8_SCHED; PG8_LDA(At, 0, 0); PG8_STAGE(PG8_SA(1, 1), a1 + hstep, voffA);
;             PG8_WAIT_V(8); PG8_WAIT_L(0); PG8_BAR; PG8_MMA(0, 0, At, B0); PG8_MMA(0, 1, At, B1); PG8_BAR; PG8_SCHED;
;             PG8_LDA(At, 0, 1); PG8_STAGE(PG8_SB(0, 0), b2, voffB); PG8_STAGE(PG8_SB(0, 1), b2 + hstep, voffB); PG8_STAGE(PG8_SA(0, 0), a2, voffA);
.LBB0_369:
	ds_read_b128 v[128:131], v169
	ds_read_b128 v[150:153], v169 offset:1024
	ds_read_b128 v[154:157], v169 offset:2048
	ds_read_b128 v[158:161], v169 offset:3072
	ds_read_b128 v[176:179], v172
	ds_read_b128 v[180:183], v172 offset:1024
	ds_read_b128 v[184:187], v172 offset:2048
	ds_read_b128 v[188:191], v172 offset:3072
	s_add_u32 s36, s0, 0xfffc0080
	s_addc_u32 s37, s1, -1
	s_cmp_eq_u32 s53, 12
	s_cselect_b32 s39, s7, s37
	s_cselect_b32 s38, s27, s36
	s_cselect_b32 s37, s25, s52
	s_cselect_b32 s36, s33, s51
	v_lshl_add_u64 v[162:163], s[0:1], 0, v[142:143]
	s_add_i32 m0, s35, 0xc000
	ds_read_b128 v[202:205], v173
	ds_read_b128 v[206:209], v173 offset:1024
	ds_read_b128 v[210:213], v173 offset:2048
	ds_read_b128 v[214:217], v173 offset:3072
	ds_read_b128 v[218:221], v173 offset:4096
	ds_read_b128 v[222:225], v173 offset:5120
	ds_read_b128 v[226:229], v173 offset:6144
	ds_read_b128 v[230:233], v173 offset:7168
	global_load_lds_dwordx4 v[162:163], off
	v_lshl_add_u64 v[162:163], s[0:1], 0, v[144:145]
	s_add_i32 m0, s35, 0xe000
	s_nop 0
	global_load_lds_dwordx4 v[162:163], off
	s_waitcnt vmcnt(8)
	s_waitcnt lgkmcnt(0)
	s_barrier
	s_setprio 1
	s_waitcnt lgkmcnt(0)
	v_mfma_f32_16x16x32_bf16 v[124:127], v[128:131], v[202:205], v[124:127]
	v_mfma_f32_16x16x32_bf16 v[120:123], v[154:157], v[202:205], v[120:123]
	v_mfma_f32_16x16x32_bf16 v[108:111], v[128:131], v[210:213], v[108:111]
	v_mfma_f32_16x16x32_bf16 v[104:107], v[154:157], v[210:213], v[104:107]
	v_mfma_f32_16x16x32_bf16 v[92:95], v[128:131], v[218:221], v[92:95]
	v_mfma_f32_16x16x32_bf16 v[88:91], v[154:157], v[218:221], v[88:91]
	v_mfma_f32_16x16x32_bf16 v[76:79], v[128:131], v[226:229], v[76:79]
	v_mfma_f32_16x16x32_bf16 v[72:75], v[154:157], v[226:229], v[72:75]
	v_mfma_f32_16x16x32_bf16 v[124:127], v[150:153], v[206:209], v[124:127]
	v_mfma_f32_16x16x32_bf16 v[120:123], v[158:161], v[206:209], v[120:123]
	v_mfma_f32_16x16x32_bf16 v[108:111], v[150:153], v[214:217], v[108:111]
	v_mfma_f32_16x16x32_bf16 v[104:107], v[158:161], v[214:217], v[104:107]
	v_mfma_f32_16x16x32_bf16 v[92:95], v[150:153], v[222:225], v[92:95]
	v_mfma_f32_16x16x32_bf16 v[88:91], v[158:161], v[222:225], v[88:91]
	v_mfma_f32_16x16x32_bf16 v[76:79], v[150:153], v[230:233], v[76:79]
	v_mfma_f32_16x16x32_bf16 v[72:75], v[158:161], v[230:233], v[72:75]
	s_setprio 0
	s_setprio 1
	v_mfma_f32_16x16x32_bf16 v[116:119], v[176:179], v[202:205], v[116:119]
	v_mfma_f32_16x16x32_bf16 v[112:115], v[184:187], v[202:205], v[112:115]
	v_mfma_f32_16x16x32_bf16 v[100:103], v[176:179], v[210:213], v[100:103]
	v_mfma_f32_16x16x32_bf16 v[96:99], v[184:187], v[210:213], v[96:99]
	v_mfma_f32_16x16x32_bf16 v[84:87], v[176:179], v[218:221], v[84:87]
	v_mfma_f32_16x16x32_bf16 v[80:83], v[184:187], v[218:221], v[80:83]
	v_mfma_f32_16x16x32_bf16 v[68:71], v[176:179], v[226:229], v[68:71]
	v_mfma_f32_16x16x32_bf16 v[64:67], v[184:187], v[226:229], v[64:67]
	v_mfma_f32_16x16x32_bf16 v[116:119], v[180:183], v[206:209], v[116:119]
	v_mfma_f32_16x16x32_bf16 v[112:115], v[188:191], v[206:209], v[112:115]
	v_mfma_f32_16x16x32_bf16 v[100:103], v[180:183], v[214:217], v[100:103]
	v_mfma_f32_16x16x32_bf16 v[96:99], v[188:191], v[214:217], v[96:99]
	v_mfma_f32_16x16x32_bf16 v[84:87], v[180:183], v[222:225], v[84:87]
	v_mfma_f32_16x16x32_bf16 v[80:83], v[188:191], v[222:225], v[80:83]
	v_mfma_f32_16x16x32_bf16 v[68:71], v[180:183], v[230:233], v[68:71]
	v_mfma_f32_16x16x32_bf16 v[64:67], v[188:191], v[230:233], v[64:67]
	s_setprio 0
	s_barrier
	s_setprio 2
	s_add_i32 s54, s49, s40
	v_lshl_add_u64 v[162:163], s[36:37], 0, v[134:135]
	s_mov_b32 m0, s54
	ds_read_b128 v[202:205], v173 offset:16384
	ds_read_b128 v[206:209], v173 offset:17408
	ds_read_b128 v[210:213], v173 offset:18432
	ds_read_b128 v[214:217], v173 offset:19456
	ds_read_b128 v[218:221], v173 offset:20480
	ds_read_b128 v[222:225], v173 offset:21504
	ds_read_b128 v[226:229], v173 offset:22528
	ds_read_b128 v[230:233], v173 offset:23552
	global_load_lds_dwordx4 v[162:163], off
	s_add_i32 m0, s54, 0x2000
	s_add_u32 s54, s36, 0x40000
	v_lshl_add_u64 v[192:193], s[36:37], 0, v[138:139]
	s_addc_u32 s55, s37, 0
	s_add_i32 s56, s50, s40
	global_load_lds_dwordx4 v[192:193], off
	v_lshl_add_u64 v[196:197], s[54:55], 0, v[134:135]
	s_mov_b32 m0, s56
	v_lshl_add_u64 v[234:235], s[38:39], 0, v[136:137]
	global_load_lds_dwordx4 v[196:197], off
	v_lshl_add_u64 v[196:197], s[54:55], 0, v[138:139]
	s_add_i32 m0, s56, 0x2000
	s_nop 0
	global_load_lds_dwordx4 v[196:197], off
	v_lshl_add_u64 v[196:197], s[38:39], 0, v[132:133]
	s_mov_b32 m0, s35
	s_nop 0
	global_load_lds_dwordx4 v[196:197], off
	s_mov_b32 m0, s41
	s_nop 0
	global_load_lds_dwordx4 v[234:235], off
	s_waitcnt vmcnt(8)
	s_waitcnt lgkmcnt(0)
	s_barrier
; #define PG8_STAGE(bufoff, gbase, voff) do { _Pragma("unroll") for (int _i = 0; _i < 2; ++_i) \
;         __builtin_amdgcn_global_load_lds((const unsigned*)((const char*)(gbase) + (voff)[_i]), (PG8_LAS unsigned*)(lds + (bufoff) + ldsw + _i * 8192), 16, 0, 0); } while (0)
; #define PG8_LDA(dst, b, h) do { _Pragma("unroll") for (int m = 0; m < 4; ++m) _Pragma("unroll") for (int k = 0; k < 2; ++k) dst[m][k] = *(const PG8_LAS bf16x8*)(lds + PG8_SA(b, h) + aoff + m * 2048 + k * 1024); } while (0)
; #define PG8_LDB(dst, b, h) do { _Pragma("unroll") for (int n = 0; n < 2; ++n) _Pragma("unroll") for (int k = 0; k < 2; ++k) dst[n][k] = *(const PG8_LAS bf16x8*)(lds + PG8_SB(b, h) + boff + n * 2048 + k * 1024); } while (0)
; #define PG8_MMA(ai, bj, At, Bt) do { __builtin_amdgcn_s_setprio(1); _Pragma("unroll") for (int m = 0; m < 4; ++m) _Pragma("unroll") for (int n = 0; n < 2; ++n) _Pragma("unroll") for (int k = 0; k < 2; ++k) \
;         acc[ai][bj][m][n] = __builtin_amdgcn_mfma_f32_16x16x32_bf16(Bt[n][k], At[m][k], acc[ai][bj][m][n], 0, 0, 0); __builtin_amdgcn_s_setprio(0); } while (0)
; #define PG8_WAIT_V(n) asm volatile("s_waitcnt vmcnt(" #n ")" ::: "memory")
; #define PG8_WAIT_L(n) asm volatile("s_waitcnt lgkmcnt(" #n ")" ::: "memory")
; #define PG8_BAR __builtin_amdgcn_s_barrier()
; #define PG8_SCHED __builtin_amdgcn_sched_barrier(0)
; template <class Epi, class Sched, bool ALIGN_EPI = false, bool SP2 = false>
; __device__ __forceinline__ void gemm_phase(PG8_LAS unsigned char* lds, const Gemm g, const Sched& S, const Epi& E) {
;     ...
;             PG8_WAIT_V(8); PG8_WAIT_L(0); PG8_BAR; PG8_MMA(1, 0, At, B0); PG8_MMA(1, 1, At, B1); PG8_BAR; PG8_SCHED;
;             PG8_LDB(B0, 1, 0); PG8_LDB(B1, 1, 1); PG8_SCHED; PG8_LDA(At, 1, 0); PG8_STAGE(PG8_SA(0, 1), a2 + hstep, voffA);
;             PG8_WAIT_V(8); PG8_WAIT_L(0); PG8_BAR; PG8_MMA(0, 0, At, B0); PG8_MMA(0, 1, At, B1); PG8_BAR; PG8_SCHED;
	s_setprio 1
	s_waitcnt lgkmcnt(0)
	v_mfma_f32_16x16x32_bf16 v[60:63], v[128:131], v[202:205], v[60:63]
	v_mfma_f32_16x16x32_bf16 v[56:59], v[154:157], v[202:205], v[56:59]
	v_mfma_f32_16x16x32_bf16 v[44:47], v[128:131], v[210:213], v[44:47]
	v_mfma_f32_16x16x32_bf16 v[40:43], v[154:157], v[210:213], v[40:43]
	v_mfma_f32_16x16x32_bf16 v[28:31], v[128:131], v[218:221], v[28:31]
	v_mfma_f32_16x16x32_bf16 v[24:27], v[154:157], v[218:221], v[24:27]
	v_mfma_f32_16x16x32_bf16 v[12:15], v[128:131], v[226:229], v[12:15]
	v_mfma_f32_16x16x32_bf16 v[8:11], v[154:157], v[226:229], v[8:11]
	v_mfma_f32_16x16x32_bf16 v[60:63], v[150:153], v[206:209], v[60:63]
	v_mfma_f32_16x16x32_bf16 v[56:59], v[158:161], v[206:209], v[56:59]
	v_mfma_f32_16x16x32_bf16 v[44:47], v[150:153], v[214:217], v[44:47]
	v_mfma_f32_16x16x32_bf16 v[40:43], v[158:161], v[214:217], v[40:43]
	v_mfma_f32_16x16x32_bf16 v[28:31], v[150:153], v[222:225], v[28:31]
	v_mfma_f32_16x16x32_bf16 v[24:27], v[158:161], v[222:225], v[24:27]
	v_mfma_f32_16x16x32_bf16 v[12:15], v[150:153], v[230:233], v[12:15]
	v_mfma_f32_16x16x32_bf16 v[8:11], v[158:161], v[230:233], v[8:11]
	s_setprio 0
	s_setprio 1
	v_mfma_f32_16x16x32_bf16 v[52:55], v[176:179], v[202:205], v[52:55]
	v_mfma_f32_16x16x32_bf16 v[48:51], v[184:187], v[202:205], v[48:51]
	v_mfma_f32_16x16x32_bf16 v[36:39], v[176:179], v[210:213], v[36:39]
	v_mfma_f32_16x16x32_bf16 v[32:35], v[184:187], v[210:213], v[32:35]
	v_mfma_f32_16x16x32_bf16 v[20:23], v[176:179], v[218:221], v[20:23]
	v_mfma_f32_16x16x32_bf16 v[16:19], v[184:187], v[218:221], v[16:19]
	v_mfma_f32_16x16x32_bf16 v[4:7], v[176:179], v[226:229], v[4:7]
	v_mfma_f32_16x16x32_bf16 v[0:3], v[184:187], v[226:229], v[0:3]
	v_mfma_f32_16x16x32_bf16 v[52:55], v[180:183], v[206:209], v[52:55]
	v_mfma_f32_16x16x32_bf16 v[48:51], v[188:191], v[206:209], v[48:51]
	v_mfma_f32_16x16x32_bf16 v[36:39], v[180:183], v[214:217], v[36:39]
	v_mfma_f32_16x16x32_bf16 v[32:35], v[188:191], v[214:217], v[32:35]
	v_mfma_f32_16x16x32_bf16 v[20:23], v[180:183], v[222:225], v[20:23]
	v_mfma_f32_16x16x32_bf16 v[16:19], v[188:191], v[222:225], v[16:19]
	v_mfma_f32_16x16x32_bf16 v[4:7], v[180:183], v[230:233], v[4:7]
	v_mfma_f32_16x16x32_bf16 v[0:3], v[188:191], v[230:233], v[0:3]
	s_setprio 0
	s_barrier
	s_add_i32 s54, 0, 0x18000
	v_add_u32_e32 v140, s54, v165
	s_add_i32 s55, 0, 0x1c000
	ds_read_b128 v[128:131], v140
	ds_read_b128 v[150:153], v140 offset:1024
	ds_read_b128 v[154:157], v140 offset:2048
	ds_read_b128 v[158:161], v140 offset:3072
	v_add_u32_e32 v140, s55, v165
	ds_read_b128 v[176:179], v140
	ds_read_b128 v[180:183], v140 offset:1024
	ds_read_b128 v[184:187], v140 offset:2048
	ds_read_b128 v[188:191], v140 offset:3072
	s_add_u32 s38, s38, 0x40000
	s_addc_u32 s39, s39, 0
	s_mov_b32 m0, s42
	v_lshl_add_u64 v[236:237], s[38:39], 0, v[132:133]
	ds_read_b128 v[202:205], v173 offset:32768
	ds_read_b128 v[206:209], v173 offset:33792
	ds_read_b128 v[210:213], v173 offset:34816
	ds_read_b128 v[214:217], v173 offset:35840
	ds_read_b128 v[218:221], v173 offset:36864
	ds_read_b128 v[222:225], v173 offset:37888
	ds_read_b128 v[226:229], v173 offset:38912
	ds_read_b128 v[230:233], v173 offset:39936
	global_load_lds_dwordx4 v[236:237], off
	v_lshl_add_u64 v[236:237], s[38:39], 0, v[136:137]
	s_mov_b32 m0, s43
	s_nop 0
	global_load_lds_dwordx4 v[236:237], off
	s_waitcnt vmcnt(8)
	s_waitcnt lgkmcnt(0)
	s_barrier
	s_setprio 1
	s_waitcnt lgkmcnt(0)
	v_mfma_f32_16x16x32_bf16 v[124:127], v[128:131], v[202:205], v[124:127]
	v_mfma_f32_16x16x32_bf16 v[120:123], v[154:157], v[202:205], v[120:123]
	v_mfma_f32_16x16x32_bf16 v[108:111], v[128:131], v[210:213], v[108:111]
	v_mfma_f32_16x16x32_bf16 v[104:107], v[154:157], v[210:213], v[104:107]
	v_mfma_f32_16x16x32_bf16 v[92:95], v[128:131], v[218:221], v[92:95]
	v_mfma_f32_16x16x32_bf16 v[88:91], v[154:157], v[218:221], v[88:91]
	v_mfma_f32_16x16x32_bf16 v[76:79], v[128:131], v[226:229], v[76:79]
	v_mfma_f32_16x16x32_bf16 v[72:75], v[154:157], v[226:229], v[72:75]
	v_mfma_f32_16x16x32_bf16 v[124:127], v[150:153], v[206:209], v[124:127]
	v_mfma_f32_16x16x32_bf16 v[120:123], v[158:161], v[206:209], v[120:123]
	v_mfma_f32_16x16x32_bf16 v[108:111], v[150:153], v[214:217], v[108:111]
	v_mfma_f32_16x16x32_bf16 v[104:107], v[158:161], v[214:217], v[104:107]
	v_mfma_f32_16x16x32_bf16 v[92:95], v[150:153], v[222:225], v[92:95]
	v_mfma_f32_16x16x32_bf16 v[88:91], v[158:161], v[222:225], v[88:91]
	v_mfma_f32_16x16x32_bf16 v[76:79], v[150:153], v[230:233], v[76:79]
	v_mfma_f32_16x16x32_bf16 v[72:75], v[158:161], v[230:233], v[72:75]
	s_setprio 0
	s_setprio 1
	v_mfma_f32_16x16x32_bf16 v[116:119], v[176:179], v[202:205], v[116:119]
	v_mfma_f32_16x16x32_bf16 v[112:115], v[184:187], v[202:205], v[112:115]
	v_mfma_f32_16x16x32_bf16 v[100:103], v[176:179], v[210:213], v[100:103]
	v_mfma_f32_16x16x32_bf16 v[96:99], v[184:187], v[210:213], v[96:99]
	v_mfma_f32_16x16x32_bf16 v[84:87], v[176:179], v[218:221], v[84:87]
	v_mfma_f32_16x16x32_bf16 v[80:83], v[184:187], v[218:221], v[80:83]
	v_mfma_f32_16x16x32_bf16 v[68:71], v[176:179], v[226:229], v[68:71]
	v_mfma_f32_16x16x32_bf16 v[64:67], v[184:187], v[226:229], v[64:67]
	v_mfma_f32_16x16x32_bf16 v[116:119], v[180:183], v[206:209], v[116:119]
	v_mfma_f32_16x16x32_bf16 v[112:115], v[188:191], v[206:209], v[112:115]
	v_mfma_f32_16x16x32_bf16 v[100:103], v[180:183], v[214:217], v[100:103]
	v_mfma_f32_16x16x32_bf16 v[96:99], v[188:191], v[214:217], v[96:99]
	v_mfma_f32_16x16x32_bf16 v[84:87], v[180:183], v[222:225], v[84:87]
	v_mfma_f32_16x16x32_bf16 v[80:83], v[188:191], v[222:225], v[80:83]
	v_mfma_f32_16x16x32_bf16 v[68:71], v[180:183], v[230:233], v[68:71]
	v_mfma_f32_16x16x32_bf16 v[64:67], v[188:191], v[230:233], v[64:67]
	s_setprio 0
	s_barrier
; #define PG8_STAGE(bufoff, gbase, voff) do { _Pragma("unroll") for (int _i = 0; _i < 2; ++_i) \
;         __builtin_amdgcn_global_load_lds((const unsigned*)((const char*)(gbase) + (voff)[_i]), (PG8_LAS unsigned*)(lds + (bufoff) + ldsw + _i * 8192), 16, 0, 0); } while (0)
; #define PG8_LDA(dst, b, h) do { _Pragma("unroll") for (int m = 0; m < 4; ++m) _Pragma("unroll") for (int k = 0; k < 2; ++k) dst[m][k] = *(const PG8_LAS bf16x8*)(lds + PG8_SA(b, h) + aoff + m * 2048 + k * 1024); } while (0)
; #define PG8_MMA(ai, bj, At, Bt) do { __builtin_amdgcn_s_setprio(1); _Pragma("unroll") for (int m = 0; m < 4; ++m) _Pragma("unroll") for (int n = 0; n < 2; ++n) _Pragma("unroll") for (int k = 0; k < 2; ++k) \
;         acc[ai][bj][m][n] = __builtin_amdgcn_mfma_f32_16x16x32_bf16(Bt[n][k], At[m][k], acc[ai][bj][m][n], 0, 0, 0); __builtin_amdgcn_s_setprio(0); } while (0)
; #define PG8_WAIT_V(n) asm volatile("s_waitcnt vmcnt(" #n ")" ::: "memory")
; #define PG8_WAIT_L(n) asm volatile("s_waitcnt lgkmcnt(" #n ")" ::: "memory")
; #define PG8_BAR __builtin_amdgcn_s_barrier()
; #define PG8_SCHED __builtin_amdgcn_sched_barrier(0)
; template <class Epi, class Sched, bool ALIGN_EPI = false, bool SP2 = false>
; __device__ __forceinline__ void gemm_phase(PG8_LAS unsigned char* lds, const Gemm g, const Sched& S, const Epi& E) {
;     ...
;             PG8_LDA(At, 1, 1); PG8_STAGE(PG8_SB(1, 0), b3, voffB); PG8_STAGE(PG8_SB(1, 1), b3 + hstep, voffB); PG8_STAGE(PG8_SA(1, 0), a3, voffA);
;             PG8_WAIT_V(8); PG8_WAIT_L(0); PG8_BAR; PG8_MMA(1, 0, At, B0); PG8_MMA(1, 1, At, B1); PG8_BAR; PG8_SCHED;
	s_setprio 2
	s_add_i32 s38, s54, s40
	v_lshl_add_u64 v[162:163], v[162:163], 0, s[10:11]
	s_mov_b32 m0, s38
	ds_read_b128 v[202:205], v173 offset:49152
	ds_read_b128 v[206:209], v173 offset:50176
	ds_read_b128 v[210:213], v173 offset:51200
	ds_read_b128 v[214:217], v173 offset:52224
	ds_read_b128 v[218:221], v173 offset:53248
	ds_read_b128 v[222:225], v173 offset:54272
	ds_read_b128 v[226:229], v173 offset:55296
	ds_read_b128 v[230:233], v173 offset:56320
	global_load_lds_dwordx4 v[162:163], off
	s_add_i32 m0, s38, 0x2000
	s_add_u32 s36, s36, 0x40080
	v_lshl_add_u64 v[162:163], v[192:193], 0, s[10:11]
	s_addc_u32 s37, s37, 0
	s_add_i32 s38, s55, s40
	global_load_lds_dwordx4 v[162:163], off
	v_lshl_add_u64 v[162:163], s[36:37], 0, v[134:135]
	s_mov_b32 m0, s38
	s_nop 0
	global_load_lds_dwordx4 v[162:163], off
	v_lshl_add_u64 v[162:163], s[36:37], 0, v[138:139]
	s_add_i32 m0, s38, 0x2000
	s_nop 0
	global_load_lds_dwordx4 v[162:163], off
	v_lshl_add_u64 v[162:163], v[196:197], 0, s[10:11]
	s_mov_b32 m0, s45
	s_nop 0
	global_load_lds_dwordx4 v[162:163], off
	v_lshl_add_u64 v[162:163], v[234:235], 0, s[10:11]
	s_mov_b32 m0, s46
	s_nop 0
	global_load_lds_dwordx4 v[162:163], off
	s_waitcnt vmcnt(8)
	s_waitcnt lgkmcnt(0)
	s_barrier
	s_setprio 1
	s_waitcnt lgkmcnt(0)
	v_mfma_f32_16x16x32_bf16 v[60:63], v[128:131], v[202:205], v[60:63]
	v_mfma_f32_16x16x32_bf16 v[56:59], v[154:157], v[202:205], v[56:59]
	v_mfma_f32_16x16x32_bf16 v[44:47], v[128:131], v[210:213], v[44:47]
	v_mfma_f32_16x16x32_bf16 v[40:43], v[154:157], v[210:213], v[40:43]
	v_mfma_f32_16x16x32_bf16 v[28:31], v[128:131], v[218:221], v[28:31]
	v_mfma_f32_16x16x32_bf16 v[24:27], v[154:157], v[218:221], v[24:27]
	v_mfma_f32_16x16x32_bf16 v[12:15], v[128:131], v[226:229], v[12:15]
	v_mfma_f32_16x16x32_bf16 v[8:11], v[154:157], v[226:229], v[8:11]
	v_mfma_f32_16x16x32_bf16 v[60:63], v[150:153], v[206:209], v[60:63]
	v_mfma_f32_16x16x32_bf16 v[56:59], v[158:161], v[206:209], v[56:59]
	v_mfma_f32_16x16x32_bf16 v[44:47], v[150:153], v[214:217], v[44:47]
	v_mfma_f32_16x16x32_bf16 v[40:43], v[158:161], v[214:217], v[40:43]
	v_mfma_f32_16x16x32_bf16 v[28:31], v[150:153], v[222:225], v[28:31]
	v_mfma_f32_16x16x32_bf16 v[24:27], v[158:161], v[222:225], v[24:27]
	v_mfma_f32_16x16x32_bf16 v[12:15], v[150:153], v[230:233], v[12:15]
	v_mfma_f32_16x16x32_bf16 v[8:11], v[158:161], v[230:233], v[8:11]
	s_setprio 0
	s_setprio 1
	v_mfma_f32_16x16x32_bf16 v[52:55], v[176:179], v[202:205], v[52:55]
	v_mfma_f32_16x16x32_bf16 v[48:51], v[184:187], v[202:205], v[48:51]
	v_mfma_f32_16x16x32_bf16 v[36:39], v[176:179], v[210:213], v[36:39]
	v_mfma_f32_16x16x32_bf16 v[32:35], v[184:187], v[210:213], v[32:35]
	v_mfma_f32_16x16x32_bf16 v[20:23], v[176:179], v[218:221], v[20:23]
	v_mfma_f32_16x16x32_bf16 v[16:19], v[184:187], v[218:221], v[16:19]
	v_mfma_f32_16x16x32_bf16 v[4:7], v[176:179], v[226:229], v[4:7]
	v_mfma_f32_16x16x32_bf16 v[0:3], v[184:187], v[226:229], v[0:3]
	v_mfma_f32_16x16x32_bf16 v[52:55], v[180:183], v[206:209], v[52:55]
	v_mfma_f32_16x16x32_bf16 v[48:51], v[188:191], v[206:209], v[48:51]
	v_mfma_f32_16x16x32_bf16 v[36:39], v[180:183], v[214:217], v[36:39]
	v_mfma_f32_16x16x32_bf16 v[32:35], v[188:191], v[214:217], v[32:35]
	v_mfma_f32_16x16x32_bf16 v[20:23], v[180:183], v[222:225], v[20:23]
	v_mfma_f32_16x16x32_bf16 v[16:19], v[188:191], v[222:225], v[16:19]
	v_mfma_f32_16x16x32_bf16 v[4:7], v[180:183], v[230:233], v[4:7]
	v_mfma_f32_16x16x32_bf16 v[0:3], v[188:191], v[230:233], v[0:3]
	s_setprio 0
	s_barrier
	s_add_i32 s53, s53, 2
	s_add_u32 s0, s0, 0x100
	s_addc_u32 s1, s1, 0
	s_add_u32 s51, s51, 0x100
	s_addc_u32 s52, s52, 0
	s_cmp_gt_u32 s53, 13
	s_cbranch_scc0 .LBB0_369
	s_and_b64 vcc, exec, s[12:13]
	s_cbranch_vccz .LBB0_372
	s_barrier

; #define PG8_STAGE(bufoff, gbase, voff) do { _Pragma("unroll") for (int _i = 0; _i < 2; ++_i) \
;         __builtin_amdgcn_global_load_lds((const unsigned*)((const char*)(gbase) + (voff)[_i]), (PG8_LAS unsigned*)(lds + (bufoff) + ldsw + _i * 8192), 16, 0, 0); } while (0)
; #define PG8_LDA(dst, b, h) do { _Pragma("unroll") for (int m = 0; m < 4; ++m) _Pragma("unroll") for (int k = 0; k < 2; ++k) dst[m][k] = *(const PG8_LAS bf16x8*)(lds + PG8_SA(b, h) + aoff + m * 2048 + k * 1024); } while (0)
; #define PG8_LDB(dst, b, h) do { _Pragma("unroll") for (int n = 0; n < 2; ++n) _Pragma("unroll") for (int k = 0; k < 2; ++k) dst[n][k] = *(const PG8_LAS bf16x8*)(lds + PG8_SB(b, h) + boff + n * 2048 + k * 1024); } while (0)
; #define PG8_MMA(ai, bj, At, Bt) do { __builtin_amdgcn_s_setprio(1); _Pragma("unroll") for (int m = 0; m < 4; ++m) _Pragma("unroll") for (int n = 0; n < 2; ++n) _Pragma("unroll") for (int k = 0; k < 2; ++k) \
;         acc[ai][bj][m][n] = __builtin_amdgcn_mfma_f32_16x16x32_bf16(Bt[n][k], At[m][k], acc[ai][bj][m][n], 0, 0, 0); __builtin_amdgcn_s_setprio(0); } while (0)
; #define PG8_WAIT_V(n) asm volatile("s_waitcnt vmcnt(" #n ")" ::: "memory")
; #define PG8_WAIT_L(n) asm volatile("s_waitcnt lgkmcnt(" #n ")" ::: "memory")
; #define PG8_BAR __builtin_amdgcn_s_barrier()
; #define PG8_SCHED __builtin_amdgcn_sched_barrier(0)
; template <class Epi, class Sched, bool ALIGN_EPI = false, bool SP2 = false>
; __device__ __forceinline__ void gemm_phase(PG8_LAS unsigned char* lds, const Gemm g, const Sched& S, const Epi& E) {
;     ...
;             PG8_LDB(B0, 0, 0); PG8_LDB(B1, 0, 1); PG8_SCHED; PG8_LDA(At, 0, 0); PG8_STAGE(PG8_SA(1, 1), a1 + hstep, voffA);
;             PG8_WAIT_V(8); PG8_WAIT_L(0); PG8_BAR; PG8_MMA(0, 0, At, B0); PG8_MMA(0, 1, At, B1); PG8_BAR; PG8_SCHED;
;             PG8_LDA(At, 0, 1); PG8_STAGE(PG8_SB(0, 0), b2, voffB); PG8_STAGE(PG8_SB(0, 1), b2 + hstep, voffB); PG8_STAGE(PG8_SA(0, 0), a2, voffA);
;             PG8_WAIT_V(8); PG8_WAIT_L(0); PG8_BAR; PG8_MMA(1, 0, At, B0); PG8_MMA(1, 1, At, B1); PG8_BAR; PG8_SCHED;
.LBB0_699:
	ds_read_b128 v[128:131], v222
	ds_read_b128 v[132:135], v222 offset:1024
	ds_read_b128 v[136:139], v222 offset:2048
	ds_read_b128 v[140:143], v222 offset:3072
	ds_read_b128 v[144:147], v223
	ds_read_b128 v[148:151], v223 offset:1024
	ds_read_b128 v[152:155], v223 offset:2048
	ds_read_b128 v[156:159], v223 offset:3072
	s_add_u32 s34, s0, 0xfffc0080
	s_addc_u32 s35, s1, -1
	s_cmp_eq_u32 s65, 12
	s_cselect_b32 s37, s25, s35
	s_cselect_b32 s36, s31, s34
	s_cselect_b32 s35, s23, s63
	s_cselect_b32 s34, s33, s62
	v_lshl_add_u64 v[244:245], s[0:1], 0, v[182:183]
	s_add_i32 m0, s39, 0xc000
	ds_read_b128 v[160:163], v224
	ds_read_b128 v[164:167], v224 offset:1024
	ds_read_b128 v[190:193], v224 offset:2048
	ds_read_b128 v[194:197], v224 offset:3072
	ds_read_b128 v[228:231], v224 offset:4096
	ds_read_b128 v[232:235], v224 offset:5120
	ds_read_b128 v[236:239], v224 offset:6144
	ds_read_b128 v[240:243], v224 offset:7168
	global_load_lds_dwordx4 v[244:245], off
	v_lshl_add_u64 v[244:245], s[0:1], 0, v[184:185]
	s_add_i32 m0, s39, 0xe000
	s_nop 0
	global_load_lds_dwordx4 v[244:245], off
	s_waitcnt vmcnt(8)
	s_waitcnt lgkmcnt(0)
	s_barrier
	s_setprio 1
	s_waitcnt lgkmcnt(0)
	v_mfma_f32_16x16x32_bf16 v[124:127], v[128:131], v[160:163], v[124:127]
	v_mfma_f32_16x16x32_bf16 v[120:123], v[136:139], v[160:163], v[120:123]
	v_mfma_f32_16x16x32_bf16 v[108:111], v[128:131], v[190:193], v[108:111]
	v_mfma_f32_16x16x32_bf16 v[104:107], v[136:139], v[190:193], v[104:107]
	v_mfma_f32_16x16x32_bf16 v[92:95], v[128:131], v[228:231], v[92:95]
	v_mfma_f32_16x16x32_bf16 v[88:91], v[136:139], v[228:231], v[88:91]
	v_mfma_f32_16x16x32_bf16 v[76:79], v[128:131], v[236:239], v[76:79]
	v_mfma_f32_16x16x32_bf16 v[72:75], v[136:139], v[236:239], v[72:75]
	v_mfma_f32_16x16x32_bf16 v[124:127], v[132:135], v[164:167], v[124:127]
	v_mfma_f32_16x16x32_bf16 v[120:123], v[140:143], v[164:167], v[120:123]
	v_mfma_f32_16x16x32_bf16 v[108:111], v[132:135], v[194:197], v[108:111]
	v_mfma_f32_16x16x32_bf16 v[104:107], v[140:143], v[194:197], v[104:107]
	v_mfma_f32_16x16x32_bf16 v[92:95], v[132:135], v[232:235], v[92:95]
	v_mfma_f32_16x16x32_bf16 v[88:91], v[140:143], v[232:235], v[88:91]
	v_mfma_f32_16x16x32_bf16 v[76:79], v[132:135], v[240:243], v[76:79]
	v_mfma_f32_16x16x32_bf16 v[72:75], v[140:143], v[240:243], v[72:75]
	s_setprio 0
	s_setprio 1
	v_mfma_f32_16x16x32_bf16 v[116:119], v[144:147], v[160:163], v[116:119]
	v_mfma_f32_16x16x32_bf16 v[112:115], v[152:155], v[160:163], v[112:115]
	v_mfma_f32_16x16x32_bf16 v[100:103], v[144:147], v[190:193], v[100:103]
	v_mfma_f32_16x16x32_bf16 v[96:99], v[152:155], v[190:193], v[96:99]
	v_mfma_f32_16x16x32_bf16 v[84:87], v[144:147], v[228:231], v[84:87]
	v_mfma_f32_16x16x32_bf16 v[80:83], v[152:155], v[228:231], v[80:83]
	v_mfma_f32_16x16x32_bf16 v[68:71], v[144:147], v[236:239], v[68:71]
	v_mfma_f32_16x16x32_bf16 v[64:67], v[152:155], v[236:239], v[64:67]
	v_mfma_f32_16x16x32_bf16 v[116:119], v[148:151], v[164:167], v[116:119]
	v_mfma_f32_16x16x32_bf16 v[112:115], v[156:159], v[164:167], v[112:115]
	v_mfma_f32_16x16x32_bf16 v[100:103], v[148:151], v[194:197], v[100:103]
	v_mfma_f32_16x16x32_bf16 v[96:99], v[156:159], v[194:197], v[96:99]
	v_mfma_f32_16x16x32_bf16 v[84:87], v[148:151], v[232:235], v[84:87]
	v_mfma_f32_16x16x32_bf16 v[80:83], v[156:159], v[232:235], v[80:83]
	v_mfma_f32_16x16x32_bf16 v[68:71], v[148:151], v[240:243], v[68:71]
	v_mfma_f32_16x16x32_bf16 v[64:67], v[156:159], v[240:243], v[64:67]
	s_setprio 0
	s_barrier
	s_setprio 2
	s_add_i32 s66, s46, s38
	v_lshl_add_u64 v[244:245], s[34:35], 0, v[174:175]
	s_mov_b32 m0, s66
	ds_read_b128 v[160:163], v224 offset:16384
	ds_read_b128 v[164:167], v224 offset:17408
	ds_read_b128 v[190:193], v224 offset:18432
	ds_read_b128 v[194:197], v224 offset:19456
	ds_read_b128 v[228:231], v224 offset:20480
	ds_read_b128 v[232:235], v224 offset:21504
	ds_read_b128 v[236:239], v224 offset:22528
	ds_read_b128 v[240:243], v224 offset:23552
	global_load_lds_dwordx4 v[244:245], off
	s_add_i32 m0, s66, 0x2000
	s_add_u32 s66, s34, 0x40000
	v_lshl_add_u64 v[246:247], s[34:35], 0, v[178:179]
	s_addc_u32 s67, s35, 0
	s_add_i32 s68, s56, s38
	global_load_lds_dwordx4 v[246:247], off
	v_lshl_add_u64 v[248:249], s[66:67], 0, v[174:175]
	s_mov_b32 m0, s68
	v_lshl_add_u64 v[250:251], s[36:37], 0, v[176:177]
	global_load_lds_dwordx4 v[248:249], off
	v_lshl_add_u64 v[248:249], s[66:67], 0, v[178:179]
	s_add_i32 m0, s68, 0x2000
	s_nop 0
	global_load_lds_dwordx4 v[248:249], off
	v_lshl_add_u64 v[248:249], s[36:37], 0, v[172:173]
	s_mov_b32 m0, s39
	s_nop 0
	global_load_lds_dwordx4 v[248:249], off
	s_mov_b32 m0, s40
	s_nop 0
	global_load_lds_dwordx4 v[250:251], off
	s_waitcnt vmcnt(8)
	s_waitcnt lgkmcnt(0)
	s_barrier
; #define PG8_STAGE(bufoff, gbase, voff) do { _Pragma("unroll") for (int _i = 0; _i < 2; ++_i) \
;         __builtin_amdgcn_global_load_lds((const unsigned*)((const char*)(gbase) + (voff)[_i]), (PG8_LAS unsigned*)(lds + (bufoff) + ldsw + _i * 8192), 16, 0, 0); } while (0)
; #define PG8_LDA(dst, b, h) do { _Pragma("unroll") for (int m = 0; m < 4; ++m) _Pragma("unroll") for (int k = 0; k < 2; ++k) dst[m][k] = *(const PG8_LAS bf16x8*)(lds + PG8_SA(b, h) + aoff + m * 2048 + k * 1024); } while (0)
; #define PG8_LDB(dst, b, h) do { _Pragma("unroll") for (int n = 0; n < 2; ++n) _Pragma("unroll") for (int k = 0; k < 2; ++k) dst[n][k] = *(const PG8_LAS bf16x8*)(lds + PG8_SB(b, h) + boff + n * 2048 + k * 1024); } while (0)
; #define PG8_MMA(ai, bj, At, Bt) do { __builtin_amdgcn_s_setprio(1); _Pragma("unroll") for (int m = 0; m < 4; ++m) _Pragma("unroll") for (int n = 0; n < 2; ++n) _Pragma("unroll") for (int k = 0; k < 2; ++k) \
;         acc[ai][bj][m][n] = __builtin_amdgcn_mfma_f32_16x16x32_bf16(Bt[n][k], At[m][k], acc[ai][bj][m][n], 0, 0, 0); __builtin_amdgcn_s_setprio(0); } while (0)
; #define PG8_WAIT_V(n) asm volatile("s_waitcnt vmcnt(" #n ")" ::: "memory")
; #define PG8_WAIT_L(n) asm volatile("s_waitcnt lgkmcnt(" #n ")" ::: "memory")
; #define PG8_BAR __builtin_amdgcn_s_barrier()
; #define PG8_SCHED __builtin_amdgcn_sched_barrier(0)
; template <class Epi, class Sched, bool ALIGN_EPI = false, bool SP2 = false>
; __device__ __forceinline__ void gemm_phase(PG8_LAS unsigned char* lds, const Gemm g, const Sched& S, const Epi& E) {
;     ...
;             PG8_WAIT_V(8); PG8_WAIT_L(0); PG8_BAR; PG8_MMA(1, 0, At, B0); PG8_MMA(1, 1, At, B1); PG8_BAR; PG8_SCHED;
;             PG8_LDB(B0, 1, 0); PG8_LDB(B1, 1, 1); PG8_SCHED; PG8_LDA(At, 1, 0); PG8_STAGE(PG8_SA(0, 1), a2 + hstep, voffA);
;             PG8_WAIT_V(8); PG8_WAIT_L(0); PG8_BAR; PG8_MMA(0, 0, At, B0); PG8_MMA(0, 1, At, B1); PG8_BAR; PG8_SCHED;
	s_setprio 1
	s_waitcnt lgkmcnt(0)
	v_mfma_f32_16x16x32_bf16 v[60:63], v[128:131], v[160:163], v[60:63]
	v_mfma_f32_16x16x32_bf16 v[56:59], v[136:139], v[160:163], v[56:59]
	v_mfma_f32_16x16x32_bf16 v[44:47], v[128:131], v[190:193], v[44:47]
	v_mfma_f32_16x16x32_bf16 v[40:43], v[136:139], v[190:193], v[40:43]
	v_mfma_f32_16x16x32_bf16 v[28:31], v[128:131], v[228:231], v[28:31]
	v_mfma_f32_16x16x32_bf16 v[24:27], v[136:139], v[228:231], v[24:27]
	v_mfma_f32_16x16x32_bf16 v[12:15], v[128:131], v[236:239], v[12:15]
	v_mfma_f32_16x16x32_bf16 v[8:11], v[136:139], v[236:239], v[8:11]
	v_mfma_f32_16x16x32_bf16 v[60:63], v[132:135], v[164:167], v[60:63]
	v_mfma_f32_16x16x32_bf16 v[56:59], v[140:143], v[164:167], v[56:59]
	v_mfma_f32_16x16x32_bf16 v[44:47], v[132:135], v[194:197], v[44:47]
	v_mfma_f32_16x16x32_bf16 v[40:43], v[140:143], v[194:197], v[40:43]
	v_mfma_f32_16x16x32_bf16 v[28:31], v[132:135], v[232:235], v[28:31]
	v_mfma_f32_16x16x32_bf16 v[24:27], v[140:143], v[232:235], v[24:27]
	v_mfma_f32_16x16x32_bf16 v[12:15], v[132:135], v[240:243], v[12:15]
	v_mfma_f32_16x16x32_bf16 v[8:11], v[140:143], v[240:243], v[8:11]
	s_setprio 0
	s_setprio 1
	v_mfma_f32_16x16x32_bf16 v[52:55], v[144:147], v[160:163], v[52:55]
	v_mfma_f32_16x16x32_bf16 v[48:51], v[152:155], v[160:163], v[48:51]
	v_mfma_f32_16x16x32_bf16 v[36:39], v[144:147], v[190:193], v[36:39]
	v_mfma_f32_16x16x32_bf16 v[32:35], v[152:155], v[190:193], v[32:35]
	v_mfma_f32_16x16x32_bf16 v[20:23], v[144:147], v[228:231], v[20:23]
	v_mfma_f32_16x16x32_bf16 v[16:19], v[152:155], v[228:231], v[16:19]
	v_mfma_f32_16x16x32_bf16 v[4:7], v[144:147], v[236:239], v[4:7]
	v_mfma_f32_16x16x32_bf16 v[0:3], v[152:155], v[236:239], v[0:3]
	v_mfma_f32_16x16x32_bf16 v[52:55], v[148:151], v[164:167], v[52:55]
	v_mfma_f32_16x16x32_bf16 v[48:51], v[156:159], v[164:167], v[48:51]
	v_mfma_f32_16x16x32_bf16 v[36:39], v[148:151], v[194:197], v[36:39]
	v_mfma_f32_16x16x32_bf16 v[32:35], v[156:159], v[194:197], v[32:35]
	v_mfma_f32_16x16x32_bf16 v[20:23], v[148:151], v[232:235], v[20:23]
	v_mfma_f32_16x16x32_bf16 v[16:19], v[156:159], v[232:235], v[16:19]
	v_mfma_f32_16x16x32_bf16 v[4:7], v[148:151], v[240:243], v[4:7]
	v_mfma_f32_16x16x32_bf16 v[0:3], v[156:159], v[240:243], v[0:3]
	s_setprio 0
	s_barrier
	s_add_i32 s66, 0, 0x18000
	s_add_i32 s67, 0, 0x1c000
	v_add_u32_e32 v140, s66, v204
	v_add_u32_e32 v156, s67, v204
	ds_read_b128 v[128:131], v140
	ds_read_b128 v[132:135], v140 offset:1024
	ds_read_b128 v[136:139], v140 offset:2048
	ds_read_b128 v[140:143], v140 offset:3072
	ds_read_b128 v[144:147], v156
	ds_read_b128 v[148:151], v156 offset:1024
	ds_read_b128 v[152:155], v156 offset:2048
	ds_read_b128 v[156:159], v156 offset:3072
	s_add_u32 s36, s36, 0x40000
	s_addc_u32 s37, s37, 0
	s_mov_b32 m0, s41
	v_lshl_add_u64 v[252:253], s[36:37], 0, v[172:173]
	ds_read_b128 v[160:163], v224 offset:32768
	ds_read_b128 v[164:167], v224 offset:33792
	ds_read_b128 v[190:193], v224 offset:34816
	ds_read_b128 v[194:197], v224 offset:35840
	ds_read_b128 v[228:231], v224 offset:36864
	ds_read_b128 v[232:235], v224 offset:37888
	ds_read_b128 v[236:239], v224 offset:38912
	ds_read_b128 v[240:243], v224 offset:39936
	global_load_lds_dwordx4 v[252:253], off
	v_lshl_add_u64 v[252:253], s[36:37], 0, v[176:177]
	s_mov_b32 m0, s42
	s_nop 0
	global_load_lds_dwordx4 v[252:253], off
	s_waitcnt vmcnt(8)
	s_waitcnt lgkmcnt(0)
	s_barrier
	s_setprio 1
	s_waitcnt lgkmcnt(0)
	v_mfma_f32_16x16x32_bf16 v[124:127], v[128:131], v[160:163], v[124:127]
	v_mfma_f32_16x16x32_bf16 v[120:123], v[136:139], v[160:163], v[120:123]
	v_mfma_f32_16x16x32_bf16 v[108:111], v[128:131], v[190:193], v[108:111]
	v_mfma_f32_16x16x32_bf16 v[104:107], v[136:139], v[190:193], v[104:107]
	v_mfma_f32_16x16x32_bf16 v[92:95], v[128:131], v[228:231], v[92:95]
	v_mfma_f32_16x16x32_bf16 v[88:91], v[136:139], v[228:231], v[88:91]
	v_mfma_f32_16x16x32_bf16 v[76:79], v[128:131], v[236:239], v[76:79]
	v_mfma_f32_16x16x32_bf16 v[72:75], v[136:139], v[236:239], v[72:75]
	v_mfma_f32_16x16x32_bf16 v[124:127], v[132:135], v[164:167], v[124:127]
	v_mfma_f32_16x16x32_bf16 v[120:123], v[140:143], v[164:167], v[120:123]
	v_mfma_f32_16x16x32_bf16 v[108:111], v[132:135], v[194:197], v[108:111]
	v_mfma_f32_16x16x32_bf16 v[104:107], v[140:143], v[194:197], v[104:107]
	v_mfma_f32_16x16x32_bf16 v[92:95], v[132:135], v[232:235], v[92:95]
	v_mfma_f32_16x16x32_bf16 v[88:91], v[140:143], v[232:235], v[88:91]
	v_mfma_f32_16x16x32_bf16 v[76:79], v[132:135], v[240:243], v[76:79]
	v_mfma_f32_16x16x32_bf16 v[72:75], v[140:143], v[240:243], v[72:75]
	s_setprio 0
	s_setprio 1
	v_mfma_f32_16x16x32_bf16 v[116:119], v[144:147], v[160:163], v[116:119]
	v_mfma_f32_16x16x32_bf16 v[112:115], v[152:155], v[160:163], v[112:115]
	v_mfma_f32_16x16x32_bf16 v[100:103], v[144:147], v[190:193], v[100:103]
	v_mfma_f32_16x16x32_bf16 v[96:99], v[152:155], v[190:193], v[96:99]
	v_mfma_f32_16x16x32_bf16 v[84:87], v[144:147], v[228:231], v[84:87]
	v_mfma_f32_16x16x32_bf16 v[80:83], v[152:155], v[228:231], v[80:83]
	v_mfma_f32_16x16x32_bf16 v[68:71], v[144:147], v[236:239], v[68:71]
	v_mfma_f32_16x16x32_bf16 v[64:67], v[152:155], v[236:239], v[64:67]
	v_mfma_f32_16x16x32_bf16 v[116:119], v[148:151], v[164:167], v[116:119]
	v_mfma_f32_16x16x32_bf16 v[112:115], v[156:159], v[164:167], v[112:115]
	v_mfma_f32_16x16x32_bf16 v[100:103], v[148:151], v[194:197], v[100:103]
	v_mfma_f32_16x16x32_bf16 v[96:99], v[156:159], v[194:197], v[96:99]
	v_mfma_f32_16x16x32_bf16 v[84:87], v[148:151], v[232:235], v[84:87]
	v_mfma_f32_16x16x32_bf16 v[80:83], v[156:159], v[232:235], v[80:83]
	v_mfma_f32_16x16x32_bf16 v[68:71], v[148:151], v[240:243], v[68:71]
	v_mfma_f32_16x16x32_bf16 v[64:67], v[156:159], v[240:243], v[64:67]
	s_setprio 0
	s_barrier
; #define PG8_STAGE(bufoff, gbase, voff) do { _Pragma("unroll") for (int _i = 0; _i < 2; ++_i) \
;         __builtin_amdgcn_global_load_lds((const unsigned*)((const char*)(gbase) + (voff)[_i]), (PG8_LAS unsigned*)(lds + (bufoff) + ldsw + _i * 8192), 16, 0, 0); } while (0)
; #define PG8_LDA(dst, b, h) do { _Pragma("unroll") for (int m = 0; m < 4; ++m) _Pragma("unroll") for (int k = 0; k < 2; ++k) dst[m][k] = *(const PG8_LAS bf16x8*)(lds + PG8_SA(b, h) + aoff + m * 2048 + k * 1024); } while (0)
; #define PG8_MMA(ai, bj, At, Bt) do { __builtin_amdgcn_s_setprio(1); _Pragma("unroll") for (int m = 0; m < 4; ++m) _Pragma("unroll") for (int n = 0; n < 2; ++n) _Pragma("unroll") for (int k = 0; k < 2; ++k) \
;         acc[ai][bj][m][n] = __builtin_amdgcn_mfma_f32_16x16x32_bf16(Bt[n][k], At[m][k], acc[ai][bj][m][n], 0, 0, 0); __builtin_amdgcn_s_setprio(0); } while (0)
; #define PG8_WAIT_V(n) asm volatile("s_waitcnt vmcnt(" #n ")" ::: "memory")
; #define PG8_WAIT_L(n) asm volatile("s_waitcnt lgkmcnt(" #n ")" ::: "memory")
; #define PG8_BAR __builtin_amdgcn_s_barrier()
; #define PG8_SCHED __builtin_amdgcn_sched_barrier(0)
; template <class Epi, class Sched, bool ALIGN_EPI = false, bool SP2 = false>
; __device__ __forceinline__ void gemm_phase(PG8_LAS unsigned char* lds, const Gemm g, const Sched& S, const Epi& E) {
;     ...
;             PG8_LDA(At, 1, 1); PG8_STAGE(PG8_SB(1, 0), b3, voffB); PG8_STAGE(PG8_SB(1, 1), b3 + hstep, voffB); PG8_STAGE(PG8_SA(1, 0), a3, voffA);
;             PG8_WAIT_V(8); PG8_WAIT_L(0); PG8_BAR; PG8_MMA(1, 0, At, B0); PG8_MMA(1, 1, At, B1); PG8_BAR; PG8_SCHED;
	s_setprio 2
	s_add_i32 s36, s66, s38
	v_lshl_add_u64 v[244:245], v[244:245], 0, s[16:17]
	s_mov_b32 m0, s36
	ds_read_b128 v[160:163], v224 offset:49152
	ds_read_b128 v[164:167], v224 offset:50176
	ds_read_b128 v[190:193], v224 offset:51200
	ds_read_b128 v[194:197], v224 offset:52224
	ds_read_b128 v[228:231], v224 offset:53248
	ds_read_b128 v[232:235], v224 offset:54272
	ds_read_b128 v[236:239], v224 offset:55296
	ds_read_b128 v[240:243], v224 offset:56320
	global_load_lds_dwordx4 v[244:245], off
	s_add_i32 m0, s36, 0x2000
	s_add_u32 s34, s34, 0x40080
	v_lshl_add_u64 v[244:245], v[246:247], 0, s[16:17]
	s_addc_u32 s35, s35, 0
	s_add_i32 s36, s67, s38
	global_load_lds_dwordx4 v[244:245], off
	v_lshl_add_u64 v[244:245], s[34:35], 0, v[174:175]
	s_mov_b32 m0, s36
	s_nop 0
	global_load_lds_dwordx4 v[244:245], off
	v_lshl_add_u64 v[244:245], s[34:35], 0, v[178:179]
	s_add_i32 m0, s36, 0x2000
	s_nop 0
	global_load_lds_dwordx4 v[244:245], off
	v_lshl_add_u64 v[244:245], v[248:249], 0, s[16:17]
	s_mov_b32 m0, s50
	s_nop 0
	global_load_lds_dwordx4 v[244:245], off
	v_lshl_add_u64 v[244:245], v[250:251], 0, s[16:17]
	s_mov_b32 m0, s51
	s_nop 0
	global_load_lds_dwordx4 v[244:245], off
	s_waitcnt vmcnt(8)
	s_waitcnt lgkmcnt(0)
	s_barrier
	s_setprio 1
	s_waitcnt lgkmcnt(0)
	v_mfma_f32_16x16x32_bf16 v[60:63], v[128:131], v[160:163], v[60:63]
	v_mfma_f32_16x16x32_bf16 v[56:59], v[136:139], v[160:163], v[56:59]
	v_mfma_f32_16x16x32_bf16 v[44:47], v[128:131], v[190:193], v[44:47]
	v_mfma_f32_16x16x32_bf16 v[40:43], v[136:139], v[190:193], v[40:43]
	v_mfma_f32_16x16x32_bf16 v[28:31], v[128:131], v[228:231], v[28:31]
	v_mfma_f32_16x16x32_bf16 v[24:27], v[136:139], v[228:231], v[24:27]
	v_mfma_f32_16x16x32_bf16 v[12:15], v[128:131], v[236:239], v[12:15]
	v_mfma_f32_16x16x32_bf16 v[8:11], v[136:139], v[236:239], v[8:11]
	v_mfma_f32_16x16x32_bf16 v[60:63], v[132:135], v[164:167], v[60:63]
	v_mfma_f32_16x16x32_bf16 v[56:59], v[140:143], v[164:167], v[56:59]
	v_mfma_f32_16x16x32_bf16 v[44:47], v[132:135], v[194:197], v[44:47]
	v_mfma_f32_16x16x32_bf16 v[40:43], v[140:143], v[194:197], v[40:43]
	v_mfma_f32_16x16x32_bf16 v[28:31], v[132:135], v[232:235], v[28:31]
	v_mfma_f32_16x16x32_bf16 v[24:27], v[140:143], v[232:235], v[24:27]
	v_mfma_f32_16x16x32_bf16 v[12:15], v[132:135], v[240:243], v[12:15]
	v_mfma_f32_16x16x32_bf16 v[8:11], v[140:143], v[240:243], v[8:11]
	s_setprio 0
	s_setprio 1
	v_mfma_f32_16x16x32_bf16 v[52:55], v[144:147], v[160:163], v[52:55]
	v_mfma_f32_16x16x32_bf16 v[48:51], v[152:155], v[160:163], v[48:51]
	v_mfma_f32_16x16x32_bf16 v[36:39], v[144:147], v[190:193], v[36:39]
	v_mfma_f32_16x16x32_bf16 v[32:35], v[152:155], v[190:193], v[32:35]
	v_mfma_f32_16x16x32_bf16 v[20:23], v[144:147], v[228:231], v[20:23]
	v_mfma_f32_16x16x32_bf16 v[16:19], v[152:155], v[228:231], v[16:19]
	v_mfma_f32_16x16x32_bf16 v[4:7], v[144:147], v[236:239], v[4:7]
	v_mfma_f32_16x16x32_bf16 v[0:3], v[152:155], v[236:239], v[0:3]
	v_mfma_f32_16x16x32_bf16 v[52:55], v[148:151], v[164:167], v[52:55]
	v_mfma_f32_16x16x32_bf16 v[48:51], v[156:159], v[164:167], v[48:51]
	v_mfma_f32_16x16x32_bf16 v[36:39], v[148:151], v[194:197], v[36:39]
	v_mfma_f32_16x16x32_bf16 v[32:35], v[156:159], v[194:197], v[32:35]
	v_mfma_f32_16x16x32_bf16 v[20:23], v[148:151], v[232:235], v[20:23]
	v_mfma_f32_16x16x32_bf16 v[16:19], v[156:159], v[232:235], v[16:19]
	v_mfma_f32_16x16x32_bf16 v[4:7], v[148:151], v[240:243], v[4:7]
	v_mfma_f32_16x16x32_bf16 v[0:3], v[156:159], v[240:243], v[0:3]
	s_setprio 0
	s_barrier
	s_add_i32 s65, s65, 2
	s_add_u32 s0, s0, 0x100
	s_addc_u32 s1, s1, 0
	s_add_u32 s62, s62, 0x100
	s_addc_u32 s63, s63, 0
	s_cmp_gt_u32 s65, 13
	s_cbranch_scc0 .LBB0_699
	s_and_b64 vcc, exec, s[18:19]
	s_cbranch_vccz .LBB0_702
	s_barrier

; #define PG8_STAGE(bufoff, gbase, voff) do { _Pragma("unroll") for (int _i = 0; _i < 2; ++_i) \
;         __builtin_amdgcn_global_load_lds((const unsigned*)((const char*)(gbase) + (voff)[_i]), (PG8_LAS unsigned*)(lds + (bufoff) + ldsw + _i * 8192), 16, 0, 0); } while (0)
; #define PG8_LDA(dst, b, h) do { _Pragma("unroll") for (int m = 0; m < 4; ++m) _Pragma("unroll") for (int k = 0; k < 2; ++k) dst[m][k] = *(const PG8_LAS bf16x8*)(lds + PG8_SA(b, h) + aoff + m * 2048 + k * 1024); } while (0)
; #define PG8_LDB(dst, b, h) do { _Pragma("unroll") for (int n = 0; n < 2; ++n) _Pragma("unroll") for (int k = 0; k < 2; ++k) dst[n][k] = *(const PG8_LAS bf16x8*)(lds + PG8_SB(b, h) + boff + n * 2048 + k * 1024); } while (0)
; #define PG8_MMA(ai, bj, At, Bt) do { __builtin_amdgcn_s_setprio(1); _Pragma("unroll") for (int m = 0; m < 4; ++m) _Pragma("unroll") for (int n = 0; n < 2; ++n) _Pragma("unroll") for (int k = 0; k < 2; ++k) \
;         acc[ai][bj][m][n] = __builtin_amdgcn_mfma_f32_16x16x32_bf16(Bt[n][k], At[m][k], acc[ai][bj][m][n], 0, 0, 0); __builtin_amdgcn_s_setprio(0); } while (0)
; #define PG8_WAIT_V(n) asm volatile("s_waitcnt vmcnt(" #n ")" ::: "memory")
; #define PG8_WAIT_L(n) asm volatile("s_waitcnt lgkmcnt(" #n ")" ::: "memory")
; #define PG8_BAR __builtin_amdgcn_s_barrier()
; #define PG8_SCHED __builtin_amdgcn_sched_barrier(0)
; template <class Epi, class Sched, bool ALIGN_EPI = false, bool SP2 = false>
; __device__ __forceinline__ void gemm_phase(PG8_LAS unsigned char* lds, const Gemm g, const Sched& S, const Epi& E) {
;     ...
;             PG8_LDB(B0, 0, 0); PG8_LDB(B1, 0, 1); PG8_SCHED; PG8_LDA(At, 0, 0); PG8_STAGE(PG8_SA(1, 1), a1 + hstep, voffA);
;             PG8_WAIT_V(8); PG8_WAIT_L(0); PG8_BAR; PG8_MMA(0, 0, At, B0); PG8_MMA(0, 1, At, B1); PG8_BAR; PG8_SCHED;
;             PG8_LDA(At, 0, 1); PG8_STAGE(PG8_SB(0, 0), b2, voffB); PG8_STAGE(PG8_SB(0, 1), b2 + hstep, voffB); PG8_STAGE(PG8_SA(0, 0), a2, voffA);
;             PG8_WAIT_V(8); PG8_WAIT_L(0); PG8_BAR; PG8_MMA(1, 0, At, B0); PG8_MMA(1, 1, At, B1); PG8_BAR; PG8_SCHED;
.LBB0_826:
	ds_read_b128 v[154:157], v150
	ds_read_b128 v[158:161], v150 offset:1024
	ds_read_b128 v[162:165], v150 offset:2048
	ds_read_b128 v[170:173], v150 offset:3072
	ds_read_b128 v[174:177], v151
	ds_read_b128 v[178:181], v151 offset:1024
	ds_read_b128 v[182:185], v151 offset:2048
	ds_read_b128 v[186:189], v151 offset:3072
	s_add_u32 s22, s0, 0xfffc0080
	s_addc_u32 s23, s1, -1
	s_cmp_eq_u32 s44, 12
	s_cselect_b32 s25, s15, s23
	s_cselect_b32 s24, s40, s22
	s_cselect_b32 s23, s13, s43
	s_cselect_b32 s22, s41, s42
	v_lshl_add_u64 v[144:145], s[0:1], 0, v[136:137]
	s_add_i32 m0, s21, 0xc000
	ds_read_b128 v[190:193], v152
	ds_read_b128 v[194:197], v152 offset:1024
	ds_read_b128 v[204:207], v152 offset:2048
	ds_read_b128 v[208:211], v152 offset:3072
	ds_read_b128 v[212:215], v152 offset:4096
	ds_read_b128 v[216:219], v152 offset:5120
	ds_read_b128 v[220:223], v152 offset:6144
	ds_read_b128 v[224:227], v152 offset:7168
	global_load_lds_dwordx4 v[144:145], off
	v_lshl_add_u64 v[144:145], s[0:1], 0, v[138:139]
	s_add_i32 m0, s21, 0xe000
	s_nop 0
	global_load_lds_dwordx4 v[144:145], off
	s_waitcnt vmcnt(8)
	s_waitcnt lgkmcnt(0)
	s_barrier
	s_setprio 1
	s_waitcnt lgkmcnt(0)
	v_mfma_f32_16x16x32_bf16 v[124:127], v[154:157], v[190:193], v[124:127]
	v_mfma_f32_16x16x32_bf16 v[120:123], v[162:165], v[190:193], v[120:123]
	v_mfma_f32_16x16x32_bf16 v[108:111], v[154:157], v[204:207], v[108:111]
	v_mfma_f32_16x16x32_bf16 v[104:107], v[162:165], v[204:207], v[104:107]
	v_mfma_f32_16x16x32_bf16 v[92:95], v[154:157], v[212:215], v[92:95]
	v_mfma_f32_16x16x32_bf16 v[88:91], v[162:165], v[212:215], v[88:91]
	v_mfma_f32_16x16x32_bf16 v[76:79], v[154:157], v[220:223], v[76:79]
	v_mfma_f32_16x16x32_bf16 v[72:75], v[162:165], v[220:223], v[72:75]
	v_mfma_f32_16x16x32_bf16 v[124:127], v[158:161], v[194:197], v[124:127]
	v_mfma_f32_16x16x32_bf16 v[120:123], v[170:173], v[194:197], v[120:123]
	v_mfma_f32_16x16x32_bf16 v[108:111], v[158:161], v[208:211], v[108:111]
	v_mfma_f32_16x16x32_bf16 v[104:107], v[170:173], v[208:211], v[104:107]
	v_mfma_f32_16x16x32_bf16 v[92:95], v[158:161], v[216:219], v[92:95]
	v_mfma_f32_16x16x32_bf16 v[88:91], v[170:173], v[216:219], v[88:91]
	v_mfma_f32_16x16x32_bf16 v[76:79], v[158:161], v[224:227], v[76:79]
	v_mfma_f32_16x16x32_bf16 v[72:75], v[170:173], v[224:227], v[72:75]
	s_setprio 0
	s_setprio 1
	v_mfma_f32_16x16x32_bf16 v[116:119], v[174:177], v[190:193], v[116:119]
	v_mfma_f32_16x16x32_bf16 v[112:115], v[182:185], v[190:193], v[112:115]
	v_mfma_f32_16x16x32_bf16 v[100:103], v[174:177], v[204:207], v[100:103]
	v_mfma_f32_16x16x32_bf16 v[96:99], v[182:185], v[204:207], v[96:99]
	v_mfma_f32_16x16x32_bf16 v[84:87], v[174:177], v[212:215], v[84:87]
	v_mfma_f32_16x16x32_bf16 v[80:83], v[182:185], v[212:215], v[80:83]
	v_mfma_f32_16x16x32_bf16 v[68:71], v[174:177], v[220:223], v[68:71]
	v_mfma_f32_16x16x32_bf16 v[64:67], v[182:185], v[220:223], v[64:67]
	v_mfma_f32_16x16x32_bf16 v[116:119], v[178:181], v[194:197], v[116:119]
	v_mfma_f32_16x16x32_bf16 v[112:115], v[186:189], v[194:197], v[112:115]
	v_mfma_f32_16x16x32_bf16 v[100:103], v[178:181], v[208:211], v[100:103]
	v_mfma_f32_16x16x32_bf16 v[96:99], v[186:189], v[208:211], v[96:99]
	v_mfma_f32_16x16x32_bf16 v[84:87], v[178:181], v[216:219], v[84:87]
	v_mfma_f32_16x16x32_bf16 v[80:83], v[186:189], v[216:219], v[80:83]
	v_mfma_f32_16x16x32_bf16 v[68:71], v[178:181], v[224:227], v[68:71]
	v_mfma_f32_16x16x32_bf16 v[64:67], v[186:189], v[224:227], v[64:67]
	s_setprio 0
	s_barrier
	s_setprio 2
	s_add_i32 s45, s46, s26
	v_lshl_add_u64 v[144:145], s[22:23], 0, v[132:133]
	s_mov_b32 m0, s45
	ds_read_b128 v[190:193], v152 offset:16384
	ds_read_b128 v[194:197], v152 offset:17408
	ds_read_b128 v[204:207], v152 offset:18432
	ds_read_b128 v[208:211], v152 offset:19456
	ds_read_b128 v[212:215], v152 offset:20480
	ds_read_b128 v[216:219], v152 offset:21504
	ds_read_b128 v[220:223], v152 offset:22528
	ds_read_b128 v[224:227], v152 offset:23552
	global_load_lds_dwordx4 v[144:145], off
	s_add_i32 m0, s45, 0x2000
	s_add_u32 s48, s22, 0x40000
	v_lshl_add_u64 v[166:167], s[22:23], 0, v[128:129]
	s_addc_u32 s49, s23, 0
	s_add_i32 s45, s38, s26
	global_load_lds_dwordx4 v[166:167], off
	v_lshl_add_u64 v[228:229], s[48:49], 0, v[132:133]
	s_mov_b32 m0, s45
	v_lshl_add_u64 v[230:231], s[24:25], 0, v[130:131]
	global_load_lds_dwordx4 v[228:229], off
	v_lshl_add_u64 v[228:229], s[48:49], 0, v[128:129]
	s_add_i32 m0, s45, 0x2000
	s_nop 0
	global_load_lds_dwordx4 v[228:229], off
	v_lshl_add_u64 v[228:229], s[24:25], 0, v[134:135]
	s_mov_b32 m0, s21
	s_nop 0
	global_load_lds_dwordx4 v[228:229], off
	s_mov_b32 m0, s29
	s_nop 0
	global_load_lds_dwordx4 v[230:231], off
	s_waitcnt vmcnt(8)
	s_waitcnt lgkmcnt(0)
	s_barrier
; #define PG8_STAGE(bufoff, gbase, voff) do { _Pragma("unroll") for (int _i = 0; _i < 2; ++_i) \
;         __builtin_amdgcn_global_load_lds((const unsigned*)((const char*)(gbase) + (voff)[_i]), (PG8_LAS unsigned*)(lds + (bufoff) + ldsw + _i * 8192), 16, 0, 0); } while (0)
; #define PG8_LDA(dst, b, h) do { _Pragma("unroll") for (int m = 0; m < 4; ++m) _Pragma("unroll") for (int k = 0; k < 2; ++k) dst[m][k] = *(const PG8_LAS bf16x8*)(lds + PG8_SA(b, h) + aoff + m * 2048 + k * 1024); } while (0)
; #define PG8_LDB(dst, b, h) do { _Pragma("unroll") for (int n = 0; n < 2; ++n) _Pragma("unroll") for (int k = 0; k < 2; ++k) dst[n][k] = *(const PG8_LAS bf16x8*)(lds + PG8_SB(b, h) + boff + n * 2048 + k * 1024); } while (0)
; #define PG8_MMA(ai, bj, At, Bt) do { __builtin_amdgcn_s_setprio(1); _Pragma("unroll") for (int m = 0; m < 4; ++m) _Pragma("unroll") for (int n = 0; n < 2; ++n) _Pragma("unroll") for (int k = 0; k < 2; ++k) \
;         acc[ai][bj][m][n] = __builtin_amdgcn_mfma_f32_16x16x32_bf16(Bt[n][k], At[m][k], acc[ai][bj][m][n], 0, 0, 0); __builtin_amdgcn_s_setprio(0); } while (0)
; #define PG8_WAIT_V(n) asm volatile("s_waitcnt vmcnt(" #n ")" ::: "memory")
; #define PG8_WAIT_L(n) asm volatile("s_waitcnt lgkmcnt(" #n ")" ::: "memory")
; #define PG8_BAR __builtin_amdgcn_s_barrier()
; #define PG8_SCHED __builtin_amdgcn_sched_barrier(0)
; template <class Epi, class Sched, bool ALIGN_EPI = false, bool SP2 = false>
; __device__ __forceinline__ void gemm_phase(PG8_LAS unsigned char* lds, const Gemm g, const Sched& S, const Epi& E) {
;     ...
;             PG8_WAIT_V(8); PG8_WAIT_L(0); PG8_BAR; PG8_MMA(1, 0, At, B0); PG8_MMA(1, 1, At, B1); PG8_BAR; PG8_SCHED;
;             PG8_LDB(B0, 1, 0); PG8_LDB(B1, 1, 1); PG8_SCHED; PG8_LDA(At, 1, 0); PG8_STAGE(PG8_SA(0, 1), a2 + hstep, voffA);
;             PG8_WAIT_V(8); PG8_WAIT_L(0); PG8_BAR; PG8_MMA(0, 0, At, B0); PG8_MMA(0, 1, At, B1); PG8_BAR; PG8_SCHED;
	s_setprio 1
	s_waitcnt lgkmcnt(0)
	v_mfma_f32_16x16x32_bf16 v[60:63], v[154:157], v[190:193], v[60:63]
	v_mfma_f32_16x16x32_bf16 v[56:59], v[162:165], v[190:193], v[56:59]
	v_mfma_f32_16x16x32_bf16 v[44:47], v[154:157], v[204:207], v[44:47]
	v_mfma_f32_16x16x32_bf16 v[40:43], v[162:165], v[204:207], v[40:43]
	v_mfma_f32_16x16x32_bf16 v[28:31], v[154:157], v[212:215], v[28:31]
	v_mfma_f32_16x16x32_bf16 v[24:27], v[162:165], v[212:215], v[24:27]
	v_mfma_f32_16x16x32_bf16 v[12:15], v[154:157], v[220:223], v[12:15]
	v_mfma_f32_16x16x32_bf16 v[8:11], v[162:165], v[220:223], v[8:11]
	v_mfma_f32_16x16x32_bf16 v[60:63], v[158:161], v[194:197], v[60:63]
	v_mfma_f32_16x16x32_bf16 v[56:59], v[170:173], v[194:197], v[56:59]
	v_mfma_f32_16x16x32_bf16 v[44:47], v[158:161], v[208:211], v[44:47]
	v_mfma_f32_16x16x32_bf16 v[40:43], v[170:173], v[208:211], v[40:43]
	v_mfma_f32_16x16x32_bf16 v[28:31], v[158:161], v[216:219], v[28:31]
	v_mfma_f32_16x16x32_bf16 v[24:27], v[170:173], v[216:219], v[24:27]
	v_mfma_f32_16x16x32_bf16 v[12:15], v[158:161], v[224:227], v[12:15]
	v_mfma_f32_16x16x32_bf16 v[8:11], v[170:173], v[224:227], v[8:11]
	s_setprio 0
	s_setprio 1
	v_mfma_f32_16x16x32_bf16 v[52:55], v[174:177], v[190:193], v[52:55]
	v_mfma_f32_16x16x32_bf16 v[48:51], v[182:185], v[190:193], v[48:51]
	v_mfma_f32_16x16x32_bf16 v[36:39], v[174:177], v[204:207], v[36:39]
	v_mfma_f32_16x16x32_bf16 v[32:35], v[182:185], v[204:207], v[32:35]
	v_mfma_f32_16x16x32_bf16 v[20:23], v[174:177], v[212:215], v[20:23]
	v_mfma_f32_16x16x32_bf16 v[16:19], v[182:185], v[212:215], v[16:19]
	v_mfma_f32_16x16x32_bf16 v[4:7], v[174:177], v[220:223], v[4:7]
	v_mfma_f32_16x16x32_bf16 v[0:3], v[182:185], v[220:223], v[0:3]
	v_mfma_f32_16x16x32_bf16 v[52:55], v[178:181], v[194:197], v[52:55]
	v_mfma_f32_16x16x32_bf16 v[48:51], v[186:189], v[194:197], v[48:51]
	v_mfma_f32_16x16x32_bf16 v[36:39], v[178:181], v[208:211], v[36:39]
	v_mfma_f32_16x16x32_bf16 v[32:35], v[186:189], v[208:211], v[32:35]
	v_mfma_f32_16x16x32_bf16 v[20:23], v[178:181], v[216:219], v[20:23]
	v_mfma_f32_16x16x32_bf16 v[16:19], v[186:189], v[216:219], v[16:19]
	v_mfma_f32_16x16x32_bf16 v[4:7], v[178:181], v[224:227], v[4:7]
	v_mfma_f32_16x16x32_bf16 v[0:3], v[186:189], v[224:227], v[0:3]
	s_setprio 0
	s_barrier
	s_add_i32 s45, 0, 0x18000
	v_add_u32_e32 v153, s45, v147
	s_add_i32 s47, 0, 0x1c000
	ds_read_b128 v[154:157], v153
	ds_read_b128 v[158:161], v153 offset:1024
	ds_read_b128 v[162:165], v153 offset:2048
	ds_read_b128 v[170:173], v153 offset:3072
	v_add_u32_e32 v153, s47, v147
	ds_read_b128 v[174:177], v153
	ds_read_b128 v[178:181], v153 offset:1024
	ds_read_b128 v[182:185], v153 offset:2048
	ds_read_b128 v[186:189], v153 offset:3072
	s_add_u32 s24, s24, 0x40000
	s_addc_u32 s25, s25, 0
	s_mov_b32 m0, s30
	v_lshl_add_u64 v[232:233], s[24:25], 0, v[134:135]
	ds_read_b128 v[190:193], v152 offset:32768
	ds_read_b128 v[194:197], v152 offset:33792
	ds_read_b128 v[204:207], v152 offset:34816
	ds_read_b128 v[208:211], v152 offset:35840
	ds_read_b128 v[212:215], v152 offset:36864
	ds_read_b128 v[216:219], v152 offset:37888
	ds_read_b128 v[220:223], v152 offset:38912
	ds_read_b128 v[224:227], v152 offset:39936
	global_load_lds_dwordx4 v[232:233], off
	v_lshl_add_u64 v[232:233], s[24:25], 0, v[130:131]
	s_mov_b32 m0, s31
	s_nop 0
	global_load_lds_dwordx4 v[232:233], off
	s_waitcnt vmcnt(8)
	s_waitcnt lgkmcnt(0)
	s_barrier
	s_setprio 1
	s_waitcnt lgkmcnt(0)
	v_mfma_f32_16x16x32_bf16 v[124:127], v[154:157], v[190:193], v[124:127]
	v_mfma_f32_16x16x32_bf16 v[120:123], v[162:165], v[190:193], v[120:123]
	v_mfma_f32_16x16x32_bf16 v[108:111], v[154:157], v[204:207], v[108:111]
	v_mfma_f32_16x16x32_bf16 v[104:107], v[162:165], v[204:207], v[104:107]
	v_mfma_f32_16x16x32_bf16 v[92:95], v[154:157], v[212:215], v[92:95]
	v_mfma_f32_16x16x32_bf16 v[88:91], v[162:165], v[212:215], v[88:91]
	v_mfma_f32_16x16x32_bf16 v[76:79], v[154:157], v[220:223], v[76:79]
	v_mfma_f32_16x16x32_bf16 v[72:75], v[162:165], v[220:223], v[72:75]
	v_mfma_f32_16x16x32_bf16 v[124:127], v[158:161], v[194:197], v[124:127]
	v_mfma_f32_16x16x32_bf16 v[120:123], v[170:173], v[194:197], v[120:123]
	v_mfma_f32_16x16x32_bf16 v[108:111], v[158:161], v[208:211], v[108:111]
	v_mfma_f32_16x16x32_bf16 v[104:107], v[170:173], v[208:211], v[104:107]
	v_mfma_f32_16x16x32_bf16 v[92:95], v[158:161], v[216:219], v[92:95]
	v_mfma_f32_16x16x32_bf16 v[88:91], v[170:173], v[216:219], v[88:91]
	v_mfma_f32_16x16x32_bf16 v[76:79], v[158:161], v[224:227], v[76:79]
	v_mfma_f32_16x16x32_bf16 v[72:75], v[170:173], v[224:227], v[72:75]
	s_setprio 0
	s_setprio 1
	v_mfma_f32_16x16x32_bf16 v[116:119], v[174:177], v[190:193], v[116:119]
	v_mfma_f32_16x16x32_bf16 v[112:115], v[182:185], v[190:193], v[112:115]
	v_mfma_f32_16x16x32_bf16 v[100:103], v[174:177], v[204:207], v[100:103]
	v_mfma_f32_16x16x32_bf16 v[96:99], v[182:185], v[204:207], v[96:99]
	v_mfma_f32_16x16x32_bf16 v[84:87], v[174:177], v[212:215], v[84:87]
	v_mfma_f32_16x16x32_bf16 v[80:83], v[182:185], v[212:215], v[80:83]
	v_mfma_f32_16x16x32_bf16 v[68:71], v[174:177], v[220:223], v[68:71]
	v_mfma_f32_16x16x32_bf16 v[64:67], v[182:185], v[220:223], v[64:67]
	v_mfma_f32_16x16x32_bf16 v[116:119], v[178:181], v[194:197], v[116:119]
	v_mfma_f32_16x16x32_bf16 v[112:115], v[186:189], v[194:197], v[112:115]
	v_mfma_f32_16x16x32_bf16 v[100:103], v[178:181], v[208:211], v[100:103]
	v_mfma_f32_16x16x32_bf16 v[96:99], v[186:189], v[208:211], v[96:99]
	v_mfma_f32_16x16x32_bf16 v[84:87], v[178:181], v[216:219], v[84:87]
	v_mfma_f32_16x16x32_bf16 v[80:83], v[186:189], v[216:219], v[80:83]
	v_mfma_f32_16x16x32_bf16 v[68:71], v[178:181], v[224:227], v[68:71]
	v_mfma_f32_16x16x32_bf16 v[64:67], v[186:189], v[224:227], v[64:67]
	s_setprio 0
	s_barrier
; #define PG8_STAGE(bufoff, gbase, voff) do { _Pragma("unroll") for (int _i = 0; _i < 2; ++_i) \
;         __builtin_amdgcn_global_load_lds((const unsigned*)((const char*)(gbase) + (voff)[_i]), (PG8_LAS unsigned*)(lds + (bufoff) + ldsw + _i * 8192), 16, 0, 0); } while (0)
; #define PG8_LDA(dst, b, h) do { _Pragma("unroll") for (int m = 0; m < 4; ++m) _Pragma("unroll") for (int k = 0; k < 2; ++k) dst[m][k] = *(const PG8_LAS bf16x8*)(lds + PG8_SA(b, h) + aoff + m * 2048 + k * 1024); } while (0)
; #define PG8_MMA(ai, bj, At, Bt) do { __builtin_amdgcn_s_setprio(1); _Pragma("unroll") for (int m = 0; m < 4; ++m) _Pragma("unroll") for (int n = 0; n < 2; ++n) _Pragma("unroll") for (int k = 0; k < 2; ++k) \
;         acc[ai][bj][m][n] = __builtin_amdgcn_mfma_f32_16x16x32_bf16(Bt[n][k], At[m][k], acc[ai][bj][m][n], 0, 0, 0); __builtin_amdgcn_s_setprio(0); } while (0)
; #define PG8_WAIT_V(n) asm volatile("s_waitcnt vmcnt(" #n ")" ::: "memory")
; #define PG8_WAIT_L(n) asm volatile("s_waitcnt lgkmcnt(" #n ")" ::: "memory")
; #define PG8_BAR __builtin_amdgcn_s_barrier()
; #define PG8_SCHED __builtin_amdgcn_sched_barrier(0)
; template <class Epi, class Sched, bool ALIGN_EPI = false, bool SP2 = false>
; __device__ __forceinline__ void gemm_phase(PG8_LAS unsigned char* lds, const Gemm g, const Sched& S, const Epi& E) {
;     ...
;             PG8_LDA(At, 1, 1); PG8_STAGE(PG8_SB(1, 0), b3, voffB); PG8_STAGE(PG8_SB(1, 1), b3 + hstep, voffB); PG8_STAGE(PG8_SA(1, 0), a3, voffA);
;             PG8_WAIT_V(8); PG8_WAIT_L(0); PG8_BAR; PG8_MMA(1, 0, At, B0); PG8_MMA(1, 1, At, B1); PG8_BAR; PG8_SCHED;
	s_setprio 2
	s_add_i32 s24, s45, s26
	v_lshl_add_u64 v[144:145], v[144:145], 0, s[8:9]
	s_mov_b32 m0, s24
	ds_read_b128 v[190:193], v152 offset:49152
	ds_read_b128 v[194:197], v152 offset:50176
	ds_read_b128 v[204:207], v152 offset:51200
	ds_read_b128 v[208:211], v152 offset:52224
	ds_read_b128 v[212:215], v152 offset:53248
	ds_read_b128 v[216:219], v152 offset:54272
	ds_read_b128 v[220:223], v152 offset:55296
	ds_read_b128 v[224:227], v152 offset:56320
	global_load_lds_dwordx4 v[144:145], off
	s_add_i32 m0, s24, 0x2000
	s_add_u32 s22, s22, 0x40080
	v_lshl_add_u64 v[144:145], v[166:167], 0, s[8:9]
	s_addc_u32 s23, s23, 0
	s_add_i32 s24, s47, s26
	global_load_lds_dwordx4 v[144:145], off
	v_lshl_add_u64 v[144:145], s[22:23], 0, v[132:133]
	s_mov_b32 m0, s24
	s_nop 0
	global_load_lds_dwordx4 v[144:145], off
	v_lshl_add_u64 v[144:145], s[22:23], 0, v[128:129]
	s_add_i32 m0, s24, 0x2000
	s_nop 0
	global_load_lds_dwordx4 v[144:145], off
	v_lshl_add_u64 v[144:145], v[228:229], 0, s[8:9]
	s_mov_b32 m0, s35
	s_nop 0
	global_load_lds_dwordx4 v[144:145], off
	v_lshl_add_u64 v[144:145], v[230:231], 0, s[8:9]
	s_mov_b32 m0, s36
	s_nop 0
	global_load_lds_dwordx4 v[144:145], off
	s_waitcnt vmcnt(8)
	s_waitcnt lgkmcnt(0)
	s_barrier
	s_setprio 1
	s_waitcnt lgkmcnt(0)
	v_mfma_f32_16x16x32_bf16 v[60:63], v[154:157], v[190:193], v[60:63]
	v_mfma_f32_16x16x32_bf16 v[56:59], v[162:165], v[190:193], v[56:59]
	v_mfma_f32_16x16x32_bf16 v[44:47], v[154:157], v[204:207], v[44:47]
	v_mfma_f32_16x16x32_bf16 v[40:43], v[162:165], v[204:207], v[40:43]
	v_mfma_f32_16x16x32_bf16 v[28:31], v[154:157], v[212:215], v[28:31]
	v_mfma_f32_16x16x32_bf16 v[24:27], v[162:165], v[212:215], v[24:27]
	v_mfma_f32_16x16x32_bf16 v[12:15], v[154:157], v[220:223], v[12:15]
	v_mfma_f32_16x16x32_bf16 v[8:11], v[162:165], v[220:223], v[8:11]
	v_mfma_f32_16x16x32_bf16 v[60:63], v[158:161], v[194:197], v[60:63]
	v_mfma_f32_16x16x32_bf16 v[56:59], v[170:173], v[194:197], v[56:59]
	v_mfma_f32_16x16x32_bf16 v[44:47], v[158:161], v[208:211], v[44:47]
	v_mfma_f32_16x16x32_bf16 v[40:43], v[170:173], v[208:211], v[40:43]
	v_mfma_f32_16x16x32_bf16 v[28:31], v[158:161], v[216:219], v[28:31]
	v_mfma_f32_16x16x32_bf16 v[24:27], v[170:173], v[216:219], v[24:27]
	v_mfma_f32_16x16x32_bf16 v[12:15], v[158:161], v[224:227], v[12:15]
	v_mfma_f32_16x16x32_bf16 v[8:11], v[170:173], v[224:227], v[8:11]
	s_setprio 0
	s_setprio 1
	v_mfma_f32_16x16x32_bf16 v[52:55], v[174:177], v[190:193], v[52:55]
	v_mfma_f32_16x16x32_bf16 v[48:51], v[182:185], v[190:193], v[48:51]
	v_mfma_f32_16x16x32_bf16 v[36:39], v[174:177], v[204:207], v[36:39]
	v_mfma_f32_16x16x32_bf16 v[32:35], v[182:185], v[204:207], v[32:35]
	v_mfma_f32_16x16x32_bf16 v[20:23], v[174:177], v[212:215], v[20:23]
	v_mfma_f32_16x16x32_bf16 v[16:19], v[182:185], v[212:215], v[16:19]
	v_mfma_f32_16x16x32_bf16 v[4:7], v[174:177], v[220:223], v[4:7]
	v_mfma_f32_16x16x32_bf16 v[0:3], v[182:185], v[220:223], v[0:3]
	v_mfma_f32_16x16x32_bf16 v[52:55], v[178:181], v[194:197], v[52:55]
	v_mfma_f32_16x16x32_bf16 v[48:51], v[186:189], v[194:197], v[48:51]
	v_mfma_f32_16x16x32_bf16 v[36:39], v[178:181], v[208:211], v[36:39]
	v_mfma_f32_16x16x32_bf16 v[32:35], v[186:189], v[208:211], v[32:35]
	v_mfma_f32_16x16x32_bf16 v[20:23], v[178:181], v[216:219], v[20:23]
	v_mfma_f32_16x16x32_bf16 v[16:19], v[186:189], v[216:219], v[16:19]
	v_mfma_f32_16x16x32_bf16 v[4:7], v[178:181], v[224:227], v[4:7]
	v_mfma_f32_16x16x32_bf16 v[0:3], v[186:189], v[224:227], v[0:3]
	s_setprio 0
	s_barrier
	s_add_i32 s44, s44, 2
	s_add_u32 s0, s0, 0x100
	s_addc_u32 s1, s1, 0
	s_add_u32 s42, s42, 0x100
	s_addc_u32 s43, s43, 0
	s_cmp_gt_u32 s44, 13
	s_cbranch_scc0 .LBB0_826
	s_and_b64 vcc, exec, s[10:11]
	s_cbranch_vccz .LBB0_829
	s_barrier

; #define PG8_STAGE(bufoff, gbase, voff) do { _Pragma("unroll") for (int _i = 0; _i < 2; ++_i) \
;         __builtin_amdgcn_global_load_lds((const unsigned*)((const char*)(gbase) + (voff)[_i]), (PG8_LAS unsigned*)(lds + (bufoff) + ldsw + _i * 8192), 16, 0, 0); } while (0)
; #define PG8_LDA(dst, b, h) do { _Pragma("unroll") for (int m = 0; m < 4; ++m) _Pragma("unroll") for (int k = 0; k < 2; ++k) dst[m][k] = *(const PG8_LAS bf16x8*)(lds + PG8_SA(b, h) + aoff + m * 2048 + k * 1024); } while (0)
; #define PG8_LDB(dst, b, h) do { _Pragma("unroll") for (int n = 0; n < 2; ++n) _Pragma("unroll") for (int k = 0; k < 2; ++k) dst[n][k] = *(const PG8_LAS bf16x8*)(lds + PG8_SB(b, h) + boff + n * 2048 + k * 1024); } while (0)
; #define PG8_MMA(ai, bj, At, Bt) do { __builtin_amdgcn_s_setprio(1); _Pragma("unroll") for (int m = 0; m < 4; ++m) _Pragma("unroll") for (int n = 0; n < 2; ++n) _Pragma("unroll") for (int k = 0; k < 2; ++k) \
;         acc[ai][bj][m][n] = __builtin_amdgcn_mfma_f32_16x16x32_bf16(Bt[n][k], At[m][k], acc[ai][bj][m][n], 0, 0, 0); __builtin_amdgcn_s_setprio(0); } while (0)
; #define PG8_WAIT_V(n) asm volatile("s_waitcnt vmcnt(" #n ")" ::: "memory")
; #define PG8_WAIT_L(n) asm volatile("s_waitcnt lgkmcnt(" #n ")" ::: "memory")
; #define PG8_BAR __builtin_amdgcn_s_barrier()
; #define PG8_SCHED __builtin_amdgcn_sched_barrier(0)
; template <class Epi, class Sched, bool ALIGN_EPI = false, bool SP2 = false>
; __device__ __forceinline__ void gemm_phase(PG8_LAS unsigned char* lds, const Gemm g, const Sched& S, const Epi& E) {
;     ...
;             PG8_LDB(B0, 0, 0); PG8_LDB(B1, 0, 1); PG8_SCHED; PG8_LDA(At, 0, 0); PG8_STAGE(PG8_SA(1, 1), a1 + hstep, voffA);
;             PG8_WAIT_V(8); PG8_WAIT_L(0); PG8_BAR; PG8_MMA(0, 0, At, B0); PG8_MMA(0, 1, At, B1); PG8_BAR; PG8_SCHED;
;             PG8_LDA(At, 0, 1); PG8_STAGE(PG8_SB(0, 0), b2, voffB); PG8_STAGE(PG8_SB(0, 1), b2 + hstep, voffB); PG8_STAGE(PG8_SA(0, 0), a2, voffA);
;             PG8_WAIT_V(8); PG8_WAIT_L(0); PG8_BAR; PG8_MMA(1, 0, At, B0); PG8_MMA(1, 1, At, B1); PG8_BAR; PG8_SCHED;
.LBB0_908:
	ds_read_b128 v[128:131], v189
	ds_read_b128 v[132:135], v189 offset:1024
	ds_read_b128 v[136:139], v189 offset:2048
	ds_read_b128 v[140:143], v189 offset:3072
	ds_read_b128 v[144:147], v190
	ds_read_b128 v[148:151], v190 offset:1024
	ds_read_b128 v[152:155], v190 offset:2048
	ds_read_b128 v[156:159], v190 offset:3072
	s_add_u32 s24, s22, 0x100
	s_addc_u32 s25, s23, 0
	s_cmp_eq_u32 s65, 40
	s_cselect_b32 s29, s9, s25
	s_cselect_b32 s28, s8, s24
	s_cselect_b32 s27, s21, s63
	s_cselect_b32 s26, s20, s62
	v_lshl_add_u64 v[182:183], s[22:23], 0, v[170:171]
	s_add_i32 m0, s31, 0xc000
	ds_read_b128 v[178:181], v191
	ds_read_b128 v[196:199], v191 offset:1024
	ds_read_b128 v[204:207], v191 offset:2048
	ds_read_b128 v[208:211], v191 offset:3072
	ds_read_b128 v[212:215], v191 offset:4096
	ds_read_b128 v[216:219], v191 offset:5120
	ds_read_b128 v[220:223], v191 offset:6144
	ds_read_b128 v[224:227], v191 offset:7168
	global_load_lds_dwordx4 v[182:183], off
	v_lshl_add_u64 v[182:183], s[22:23], 0, v[172:173]
	s_add_i32 m0, s31, 0xe000
	s_nop 0
	global_load_lds_dwordx4 v[182:183], off
	s_waitcnt vmcnt(8)
	s_waitcnt lgkmcnt(0)
	s_barrier
	s_setprio 1
	s_waitcnt lgkmcnt(0)
	v_mfma_f32_16x16x32_bf16 v[124:127], v[128:131], v[178:181], v[124:127]
	v_mfma_f32_16x16x32_bf16 v[120:123], v[136:139], v[178:181], v[120:123]
	v_mfma_f32_16x16x32_bf16 v[108:111], v[128:131], v[204:207], v[108:111]
	v_mfma_f32_16x16x32_bf16 v[104:107], v[136:139], v[204:207], v[104:107]
	v_mfma_f32_16x16x32_bf16 v[92:95], v[128:131], v[212:215], v[92:95]
	v_mfma_f32_16x16x32_bf16 v[88:91], v[136:139], v[212:215], v[88:91]
	v_mfma_f32_16x16x32_bf16 v[76:79], v[128:131], v[220:223], v[76:79]
	v_mfma_f32_16x16x32_bf16 v[72:75], v[136:139], v[220:223], v[72:75]
	v_mfma_f32_16x16x32_bf16 v[124:127], v[132:135], v[196:199], v[124:127]
	v_mfma_f32_16x16x32_bf16 v[120:123], v[140:143], v[196:199], v[120:123]
	v_mfma_f32_16x16x32_bf16 v[108:111], v[132:135], v[208:211], v[108:111]
	v_mfma_f32_16x16x32_bf16 v[104:107], v[140:143], v[208:211], v[104:107]
	v_mfma_f32_16x16x32_bf16 v[92:95], v[132:135], v[216:219], v[92:95]
	v_mfma_f32_16x16x32_bf16 v[88:91], v[140:143], v[216:219], v[88:91]
	v_mfma_f32_16x16x32_bf16 v[76:79], v[132:135], v[224:227], v[76:79]
	v_mfma_f32_16x16x32_bf16 v[72:75], v[140:143], v[224:227], v[72:75]
	s_setprio 0
	s_setprio 1
	v_mfma_f32_16x16x32_bf16 v[116:119], v[144:147], v[178:181], v[116:119]
	v_mfma_f32_16x16x32_bf16 v[112:115], v[152:155], v[178:181], v[112:115]
	v_mfma_f32_16x16x32_bf16 v[100:103], v[144:147], v[204:207], v[100:103]
	v_mfma_f32_16x16x32_bf16 v[96:99], v[152:155], v[204:207], v[96:99]
	v_mfma_f32_16x16x32_bf16 v[84:87], v[144:147], v[212:215], v[84:87]
	v_mfma_f32_16x16x32_bf16 v[80:83], v[152:155], v[212:215], v[80:83]
	v_mfma_f32_16x16x32_bf16 v[68:71], v[144:147], v[220:223], v[68:71]
	v_mfma_f32_16x16x32_bf16 v[64:67], v[152:155], v[220:223], v[64:67]
	v_mfma_f32_16x16x32_bf16 v[116:119], v[148:151], v[196:199], v[116:119]
	v_mfma_f32_16x16x32_bf16 v[112:115], v[156:159], v[196:199], v[112:115]
	v_mfma_f32_16x16x32_bf16 v[100:103], v[148:151], v[208:211], v[100:103]
	v_mfma_f32_16x16x32_bf16 v[96:99], v[156:159], v[208:211], v[96:99]
	v_mfma_f32_16x16x32_bf16 v[84:87], v[148:151], v[216:219], v[84:87]
	v_mfma_f32_16x16x32_bf16 v[80:83], v[156:159], v[216:219], v[80:83]
	v_mfma_f32_16x16x32_bf16 v[68:71], v[148:151], v[224:227], v[68:71]
	v_mfma_f32_16x16x32_bf16 v[64:67], v[156:159], v[224:227], v[64:67]
	s_setprio 0
	s_barrier
	s_setprio 2
	s_add_i32 s22, s46, s30
	v_lshl_add_u64 v[182:183], s[26:27], 0, v[162:163]
	s_mov_b32 m0, s22
	ds_read_b128 v[178:181], v191 offset:16384
	ds_read_b128 v[196:199], v191 offset:17408
	ds_read_b128 v[204:207], v191 offset:18432
	ds_read_b128 v[208:211], v191 offset:19456
	ds_read_b128 v[212:215], v191 offset:20480
	ds_read_b128 v[216:219], v191 offset:21504
	ds_read_b128 v[220:223], v191 offset:22528
	ds_read_b128 v[224:227], v191 offset:23552
	global_load_lds_dwordx4 v[182:183], off
	s_add_i32 m0, s22, 0x2000
	s_add_u32 s22, s26, 0xb0000
	v_lshl_add_u64 v[200:201], s[26:27], 0, v[166:167]
	s_addc_u32 s23, s27, 0
	s_add_i32 s66, s47, s30
	global_load_lds_dwordx4 v[200:201], off
	v_lshl_add_u64 v[228:229], s[22:23], 0, v[162:163]
	s_mov_b32 m0, s66
	v_lshl_add_u64 v[230:231], s[28:29], 0, v[164:165]
	global_load_lds_dwordx4 v[228:229], off
	v_lshl_add_u64 v[228:229], s[22:23], 0, v[166:167]
	s_add_i32 m0, s66, 0x2000
	s_nop 0
	global_load_lds_dwordx4 v[228:229], off
	v_lshl_add_u64 v[228:229], s[28:29], 0, v[160:161]
	s_mov_b32 m0, s31
	s_nop 0
	global_load_lds_dwordx4 v[228:229], off
	s_mov_b32 m0, s33
	s_nop 0
	global_load_lds_dwordx4 v[230:231], off
	s_waitcnt vmcnt(8)
	s_waitcnt lgkmcnt(0)
	s_barrier
; #define PG8_STAGE(bufoff, gbase, voff) do { _Pragma("unroll") for (int _i = 0; _i < 2; ++_i) \
;         __builtin_amdgcn_global_load_lds((const unsigned*)((const char*)(gbase) + (voff)[_i]), (PG8_LAS unsigned*)(lds + (bufoff) + ldsw + _i * 8192), 16, 0, 0); } while (0)
; #define PG8_LDA(dst, b, h) do { _Pragma("unroll") for (int m = 0; m < 4; ++m) _Pragma("unroll") for (int k = 0; k < 2; ++k) dst[m][k] = *(const PG8_LAS bf16x8*)(lds + PG8_SA(b, h) + aoff + m * 2048 + k * 1024); } while (0)
; #define PG8_LDB(dst, b, h) do { _Pragma("unroll") for (int n = 0; n < 2; ++n) _Pragma("unroll") for (int k = 0; k < 2; ++k) dst[n][k] = *(const PG8_LAS bf16x8*)(lds + PG8_SB(b, h) + boff + n * 2048 + k * 1024); } while (0)
; #define PG8_MMA(ai, bj, At, Bt) do { __builtin_amdgcn_s_setprio(1); _Pragma("unroll") for (int m = 0; m < 4; ++m) _Pragma("unroll") for (int n = 0; n < 2; ++n) _Pragma("unroll") for (int k = 0; k < 2; ++k) \
;         acc[ai][bj][m][n] = __builtin_amdgcn_mfma_f32_16x16x32_bf16(Bt[n][k], At[m][k], acc[ai][bj][m][n], 0, 0, 0); __builtin_amdgcn_s_setprio(0); } while (0)
; #define PG8_WAIT_V(n) asm volatile("s_waitcnt vmcnt(" #n ")" ::: "memory")
; #define PG8_WAIT_L(n) asm volatile("s_waitcnt lgkmcnt(" #n ")" ::: "memory")
; #define PG8_BAR __builtin_amdgcn_s_barrier()
; #define PG8_SCHED __builtin_amdgcn_sched_barrier(0)
; template <class Epi, class Sched, bool ALIGN_EPI = false, bool SP2 = false>
; __device__ __forceinline__ void gemm_phase(PG8_LAS unsigned char* lds, const Gemm g, const Sched& S, const Epi& E) {
;     ...
;             PG8_WAIT_V(8); PG8_WAIT_L(0); PG8_BAR; PG8_MMA(1, 0, At, B0); PG8_MMA(1, 1, At, B1); PG8_BAR; PG8_SCHED;
;             PG8_LDB(B0, 1, 0); PG8_LDB(B1, 1, 1); PG8_SCHED; PG8_LDA(At, 1, 0); PG8_STAGE(PG8_SA(0, 1), a2 + hstep, voffA);
;             PG8_WAIT_V(8); PG8_WAIT_L(0); PG8_BAR; PG8_MMA(0, 0, At, B0); PG8_MMA(0, 1, At, B1); PG8_BAR; PG8_SCHED;
	s_setprio 1
	s_waitcnt lgkmcnt(0)
	v_mfma_f32_16x16x32_bf16 v[60:63], v[128:131], v[178:181], v[60:63]
	v_mfma_f32_16x16x32_bf16 v[56:59], v[136:139], v[178:181], v[56:59]
	v_mfma_f32_16x16x32_bf16 v[44:47], v[128:131], v[204:207], v[44:47]
	v_mfma_f32_16x16x32_bf16 v[40:43], v[136:139], v[204:207], v[40:43]
	v_mfma_f32_16x16x32_bf16 v[28:31], v[128:131], v[212:215], v[28:31]
	v_mfma_f32_16x16x32_bf16 v[24:27], v[136:139], v[212:215], v[24:27]
	v_mfma_f32_16x16x32_bf16 v[12:15], v[128:131], v[220:223], v[12:15]
	v_mfma_f32_16x16x32_bf16 v[8:11], v[136:139], v[220:223], v[8:11]
	v_mfma_f32_16x16x32_bf16 v[60:63], v[132:135], v[196:199], v[60:63]
	v_mfma_f32_16x16x32_bf16 v[56:59], v[140:143], v[196:199], v[56:59]
	v_mfma_f32_16x16x32_bf16 v[44:47], v[132:135], v[208:211], v[44:47]
	v_mfma_f32_16x16x32_bf16 v[40:43], v[140:143], v[208:211], v[40:43]
	v_mfma_f32_16x16x32_bf16 v[28:31], v[132:135], v[216:219], v[28:31]
	v_mfma_f32_16x16x32_bf16 v[24:27], v[140:143], v[216:219], v[24:27]
	v_mfma_f32_16x16x32_bf16 v[12:15], v[132:135], v[224:227], v[12:15]
	v_mfma_f32_16x16x32_bf16 v[8:11], v[140:143], v[224:227], v[8:11]
	s_setprio 0
	s_setprio 1
	v_mfma_f32_16x16x32_bf16 v[52:55], v[144:147], v[178:181], v[52:55]
	v_mfma_f32_16x16x32_bf16 v[48:51], v[152:155], v[178:181], v[48:51]
	v_mfma_f32_16x16x32_bf16 v[36:39], v[144:147], v[204:207], v[36:39]
	v_mfma_f32_16x16x32_bf16 v[32:35], v[152:155], v[204:207], v[32:35]
	v_mfma_f32_16x16x32_bf16 v[20:23], v[144:147], v[212:215], v[20:23]
	v_mfma_f32_16x16x32_bf16 v[16:19], v[152:155], v[212:215], v[16:19]
	v_mfma_f32_16x16x32_bf16 v[4:7], v[144:147], v[220:223], v[4:7]
	v_mfma_f32_16x16x32_bf16 v[0:3], v[152:155], v[220:223], v[0:3]
	v_mfma_f32_16x16x32_bf16 v[52:55], v[148:151], v[196:199], v[52:55]
	v_mfma_f32_16x16x32_bf16 v[48:51], v[156:159], v[196:199], v[48:51]
	v_mfma_f32_16x16x32_bf16 v[36:39], v[148:151], v[208:211], v[36:39]
	v_mfma_f32_16x16x32_bf16 v[32:35], v[156:159], v[208:211], v[32:35]
	v_mfma_f32_16x16x32_bf16 v[20:23], v[148:151], v[216:219], v[20:23]
	v_mfma_f32_16x16x32_bf16 v[16:19], v[156:159], v[216:219], v[16:19]
	v_mfma_f32_16x16x32_bf16 v[4:7], v[148:151], v[224:227], v[4:7]
	v_mfma_f32_16x16x32_bf16 v[0:3], v[156:159], v[224:227], v[0:3]
	s_setprio 0
	s_barrier
	s_add_i32 s66, 0, 0x18000
	s_add_i32 s67, 0, 0x1c000
	v_add_u32_e32 v140, s66, v185
	v_add_u32_e32 v156, s67, v185
	ds_read_b128 v[128:131], v140
	ds_read_b128 v[132:135], v140 offset:1024
	ds_read_b128 v[136:139], v140 offset:2048
	ds_read_b128 v[140:143], v140 offset:3072
	ds_read_b128 v[144:147], v156
	ds_read_b128 v[148:151], v156 offset:1024
	ds_read_b128 v[152:155], v156 offset:2048
	ds_read_b128 v[156:159], v156 offset:3072
	s_add_u32 s22, s28, 0xb0000
	s_addc_u32 s23, s29, 0
	s_mov_b32 m0, s34
	v_lshl_add_u64 v[232:233], s[22:23], 0, v[160:161]
	ds_read_b128 v[178:181], v191 offset:32768
	ds_read_b128 v[196:199], v191 offset:33792
	ds_read_b128 v[204:207], v191 offset:34816
	ds_read_b128 v[208:211], v191 offset:35840
	ds_read_b128 v[212:215], v191 offset:36864
	ds_read_b128 v[216:219], v191 offset:37888
	ds_read_b128 v[220:223], v191 offset:38912
	ds_read_b128 v[224:227], v191 offset:39936
	global_load_lds_dwordx4 v[232:233], off
	v_lshl_add_u64 v[232:233], s[22:23], 0, v[164:165]
	s_mov_b32 m0, s35
	s_nop 0
	global_load_lds_dwordx4 v[232:233], off
	s_waitcnt vmcnt(8)
	s_waitcnt lgkmcnt(0)
	s_barrier
	s_setprio 1
	s_waitcnt lgkmcnt(0)
	v_mfma_f32_16x16x32_bf16 v[124:127], v[128:131], v[178:181], v[124:127]
	v_mfma_f32_16x16x32_bf16 v[120:123], v[136:139], v[178:181], v[120:123]
	v_mfma_f32_16x16x32_bf16 v[108:111], v[128:131], v[204:207], v[108:111]
	v_mfma_f32_16x16x32_bf16 v[104:107], v[136:139], v[204:207], v[104:107]
	v_mfma_f32_16x16x32_bf16 v[92:95], v[128:131], v[212:215], v[92:95]
	v_mfma_f32_16x16x32_bf16 v[88:91], v[136:139], v[212:215], v[88:91]
	v_mfma_f32_16x16x32_bf16 v[76:79], v[128:131], v[220:223], v[76:79]
	v_mfma_f32_16x16x32_bf16 v[72:75], v[136:139], v[220:223], v[72:75]
	v_mfma_f32_16x16x32_bf16 v[124:127], v[132:135], v[196:199], v[124:127]
	v_mfma_f32_16x16x32_bf16 v[120:123], v[140:143], v[196:199], v[120:123]
	v_mfma_f32_16x16x32_bf16 v[108:111], v[132:135], v[208:211], v[108:111]
	v_mfma_f32_16x16x32_bf16 v[104:107], v[140:143], v[208:211], v[104:107]
	v_mfma_f32_16x16x32_bf16 v[92:95], v[132:135], v[216:219], v[92:95]
	v_mfma_f32_16x16x32_bf16 v[88:91], v[140:143], v[216:219], v[88:91]
	v_mfma_f32_16x16x32_bf16 v[76:79], v[132:135], v[224:227], v[76:79]
	v_mfma_f32_16x16x32_bf16 v[72:75], v[140:143], v[224:227], v[72:75]
	s_setprio 0
	s_setprio 1
	v_mfma_f32_16x16x32_bf16 v[116:119], v[144:147], v[178:181], v[116:119]
	v_mfma_f32_16x16x32_bf16 v[112:115], v[152:155], v[178:181], v[112:115]
	v_mfma_f32_16x16x32_bf16 v[100:103], v[144:147], v[204:207], v[100:103]
	v_mfma_f32_16x16x32_bf16 v[96:99], v[152:155], v[204:207], v[96:99]
	v_mfma_f32_16x16x32_bf16 v[84:87], v[144:147], v[212:215], v[84:87]
	v_mfma_f32_16x16x32_bf16 v[80:83], v[152:155], v[212:215], v[80:83]
	v_mfma_f32_16x16x32_bf16 v[68:71], v[144:147], v[220:223], v[68:71]
	v_mfma_f32_16x16x32_bf16 v[64:67], v[152:155], v[220:223], v[64:67]
	v_mfma_f32_16x16x32_bf16 v[116:119], v[148:151], v[196:199], v[116:119]
	v_mfma_f32_16x16x32_bf16 v[112:115], v[156:159], v[196:199], v[112:115]
	v_mfma_f32_16x16x32_bf16 v[100:103], v[148:151], v[208:211], v[100:103]
	v_mfma_f32_16x16x32_bf16 v[96:99], v[156:159], v[208:211], v[96:99]
	v_mfma_f32_16x16x32_bf16 v[84:87], v[148:151], v[216:219], v[84:87]
	v_mfma_f32_16x16x32_bf16 v[80:83], v[156:159], v[216:219], v[80:83]
	v_mfma_f32_16x16x32_bf16 v[68:71], v[148:151], v[224:227], v[68:71]
	v_mfma_f32_16x16x32_bf16 v[64:67], v[156:159], v[224:227], v[64:67]
	s_setprio 0
	s_barrier
; #define PG8_STAGE(bufoff, gbase, voff) do { _Pragma("unroll") for (int _i = 0; _i < 2; ++_i) \
;         __builtin_amdgcn_global_load_lds((const unsigned*)((const char*)(gbase) + (voff)[_i]), (PG8_LAS unsigned*)(lds + (bufoff) + ldsw + _i * 8192), 16, 0, 0); } while (0)
; #define PG8_LDA(dst, b, h) do { _Pragma("unroll") for (int m = 0; m < 4; ++m) _Pragma("unroll") for (int k = 0; k < 2; ++k) dst[m][k] = *(const PG8_LAS bf16x8*)(lds + PG8_SA(b, h) + aoff + m * 2048 + k * 1024); } while (0)
; #define PG8_MMA(ai, bj, At, Bt) do { __builtin_amdgcn_s_setprio(1); _Pragma("unroll") for (int m = 0; m < 4; ++m) _Pragma("unroll") for (int n = 0; n < 2; ++n) _Pragma("unroll") for (int k = 0; k < 2; ++k) \
;         acc[ai][bj][m][n] = __builtin_amdgcn_mfma_f32_16x16x32_bf16(Bt[n][k], At[m][k], acc[ai][bj][m][n], 0, 0, 0); __builtin_amdgcn_s_setprio(0); } while (0)
; #define PG8_WAIT_V(n) asm volatile("s_waitcnt vmcnt(" #n ")" ::: "memory")
; #define PG8_WAIT_L(n) asm volatile("s_waitcnt lgkmcnt(" #n ")" ::: "memory")
; #define PG8_BAR __builtin_amdgcn_s_barrier()
; #define PG8_SCHED __builtin_amdgcn_sched_barrier(0)
; template <class Epi, class Sched, bool ALIGN_EPI = false, bool SP2 = false>
; __device__ __forceinline__ void gemm_phase(PG8_LAS unsigned char* lds, const Gemm g, const Sched& S, const Epi& E) {
;     ...
;             PG8_LDA(At, 1, 1); PG8_STAGE(PG8_SB(1, 0), b3, voffB); PG8_STAGE(PG8_SB(1, 1), b3 + hstep, voffB); PG8_STAGE(PG8_SA(1, 0), a3, voffA);
;             PG8_WAIT_V(8); PG8_WAIT_L(0); PG8_BAR; PG8_MMA(1, 0, At, B0); PG8_MMA(1, 1, At, B1); PG8_BAR; PG8_SCHED;
	s_setprio 2
	s_add_i32 s22, s66, s30
	v_lshl_add_u64 v[182:183], v[182:183], 0, s[14:15]
	s_mov_b32 m0, s22
	ds_read_b128 v[178:181], v191 offset:49152
	ds_read_b128 v[196:199], v191 offset:50176
	ds_read_b128 v[204:207], v191 offset:51200
	ds_read_b128 v[208:211], v191 offset:52224
	ds_read_b128 v[212:215], v191 offset:53248
	ds_read_b128 v[216:219], v191 offset:54272
	ds_read_b128 v[220:223], v191 offset:55296
	ds_read_b128 v[224:227], v191 offset:56320
	global_load_lds_dwordx4 v[182:183], off
	s_add_i32 m0, s22, 0x2000
	s_add_u32 s22, s26, 0xb0080
	v_lshl_add_u64 v[182:183], v[200:201], 0, s[14:15]
	s_addc_u32 s23, s27, 0
	s_add_i32 s26, s67, s30
	global_load_lds_dwordx4 v[182:183], off
	v_lshl_add_u64 v[182:183], s[22:23], 0, v[162:163]
	s_mov_b32 m0, s26
	s_nop 0
	global_load_lds_dwordx4 v[182:183], off
	v_lshl_add_u64 v[182:183], s[22:23], 0, v[166:167]
	s_add_i32 m0, s26, 0x2000
	s_nop 0
	global_load_lds_dwordx4 v[182:183], off
	v_lshl_add_u64 v[182:183], v[228:229], 0, s[14:15]
	s_mov_b32 m0, s40
	s_nop 0
	global_load_lds_dwordx4 v[182:183], off
	v_lshl_add_u64 v[182:183], v[230:231], 0, s[14:15]
	s_mov_b32 m0, s41
	s_nop 0
	global_load_lds_dwordx4 v[182:183], off
	s_waitcnt vmcnt(8)
	s_waitcnt lgkmcnt(0)
	s_barrier
	s_setprio 1
	s_waitcnt lgkmcnt(0)
	v_mfma_f32_16x16x32_bf16 v[60:63], v[128:131], v[178:181], v[60:63]
	v_mfma_f32_16x16x32_bf16 v[56:59], v[136:139], v[178:181], v[56:59]
	v_mfma_f32_16x16x32_bf16 v[44:47], v[128:131], v[204:207], v[44:47]
	v_mfma_f32_16x16x32_bf16 v[40:43], v[136:139], v[204:207], v[40:43]
	v_mfma_f32_16x16x32_bf16 v[28:31], v[128:131], v[212:215], v[28:31]
	v_mfma_f32_16x16x32_bf16 v[24:27], v[136:139], v[212:215], v[24:27]
	v_mfma_f32_16x16x32_bf16 v[12:15], v[128:131], v[220:223], v[12:15]
	v_mfma_f32_16x16x32_bf16 v[8:11], v[136:139], v[220:223], v[8:11]
	v_mfma_f32_16x16x32_bf16 v[60:63], v[132:135], v[196:199], v[60:63]
	v_mfma_f32_16x16x32_bf16 v[56:59], v[140:143], v[196:199], v[56:59]
	v_mfma_f32_16x16x32_bf16 v[44:47], v[132:135], v[208:211], v[44:47]
	v_mfma_f32_16x16x32_bf16 v[40:43], v[140:143], v[208:211], v[40:43]
	v_mfma_f32_16x16x32_bf16 v[28:31], v[132:135], v[216:219], v[28:31]
	v_mfma_f32_16x16x32_bf16 v[24:27], v[140:143], v[216:219], v[24:27]
	v_mfma_f32_16x16x32_bf16 v[12:15], v[132:135], v[224:227], v[12:15]
	v_mfma_f32_16x16x32_bf16 v[8:11], v[140:143], v[224:227], v[8:11]
	s_setprio 0
	s_setprio 1
	v_mfma_f32_16x16x32_bf16 v[52:55], v[144:147], v[178:181], v[52:55]
	v_mfma_f32_16x16x32_bf16 v[48:51], v[152:155], v[178:181], v[48:51]
	v_mfma_f32_16x16x32_bf16 v[36:39], v[144:147], v[204:207], v[36:39]
	v_mfma_f32_16x16x32_bf16 v[32:35], v[152:155], v[204:207], v[32:35]
	v_mfma_f32_16x16x32_bf16 v[20:23], v[144:147], v[212:215], v[20:23]
	v_mfma_f32_16x16x32_bf16 v[16:19], v[152:155], v[212:215], v[16:19]
	v_mfma_f32_16x16x32_bf16 v[4:7], v[144:147], v[220:223], v[4:7]
	v_mfma_f32_16x16x32_bf16 v[0:3], v[152:155], v[220:223], v[0:3]
	v_mfma_f32_16x16x32_bf16 v[52:55], v[148:151], v[196:199], v[52:55]
	v_mfma_f32_16x16x32_bf16 v[48:51], v[156:159], v[196:199], v[48:51]
	v_mfma_f32_16x16x32_bf16 v[36:39], v[148:151], v[208:211], v[36:39]
	v_mfma_f32_16x16x32_bf16 v[32:35], v[156:159], v[208:211], v[32:35]
	v_mfma_f32_16x16x32_bf16 v[20:23], v[148:151], v[216:219], v[20:23]
	v_mfma_f32_16x16x32_bf16 v[16:19], v[156:159], v[216:219], v[16:19]
	v_mfma_f32_16x16x32_bf16 v[4:7], v[148:151], v[224:227], v[4:7]
	v_mfma_f32_16x16x32_bf16 v[0:3], v[156:159], v[224:227], v[0:3]
	s_setprio 0
	s_barrier
	s_add_i32 s65, s65, 2
	s_add_u32 s62, s62, 0x100
	s_addc_u32 s63, s63, 0
	s_cmp_gt_u32 s65, 41
	s_mov_b64 s[22:23], s[24:25]
	s_cbranch_scc0 .LBB0_908
	s_and_b64 vcc, exec, s[16:17]
	s_cbranch_vccz .LBB0_911
	s_barrier
